# int8 GEMM epilogues: row-scale loads stay hoisted, a vmcnt(0) per row restores the store pacing of the original code
# baseline (speedup 1.0000x reference)
.LBB0_369:
	v_lshl_or_b32 v112, s25, 8, v169
	v_ashrrev_i32_e32 v113, 31, v112
	v_lshl_add_u32 v162, s24, 8, v167
	v_readlane_b32 s64, v251, 8
	v_lshl_add_u64 v[120:121], v[112:113], 2, s[22:23]
	v_ashrrev_i32_e32 v163, 31, v162
	v_readlane_b32 s70, v251, 14
	v_readlane_b32 s71, v251, 15
	global_load_dwordx4 v[112:115], v[120:121], off
	v_cvt_f32_i32_e32 v141, v141
	v_lshl_add_u64 v[164:165], v[162:163], 2, s[70:71]
	global_load_dword v172, v[164:165], off
	global_load_dword v200, v[164:165], off offset:64
	global_load_dword v201, v[164:165], off offset:128
	global_load_dword v202, v[164:165], off offset:192
	global_load_dword v203, v[164:165], off offset:512
	global_load_dword v204, v[164:165], off offset:576
	global_load_dword v205, v[164:165], off offset:640
	global_load_dword v206, v[164:165], off offset:704
	global_load_dwordx4 v[124:127], v[120:121], off offset:512
	global_load_dwordx4 v[116:119], v[120:121], off offset:16
	s_nop 0
	global_load_dwordx4 v[120:123], v[120:121], off offset:528
	v_cvt_f32_i32_e32 v140, v140
	v_cvt_f32_i32_e32 v143, v143
	v_cvt_f32_i32_e32 v142, v142
	v_cvt_f32_i32_e32 v133, v133
	v_cvt_f32_i32_e32 v132, v132
	v_cvt_f32_i32_e32 v135, v135
	v_cvt_f32_i32_e32 v134, v134
	v_cvt_f32_i32_e32 v137, v137
	v_cvt_f32_i32_e32 v136, v136
	v_cvt_f32_i32_e32 v131, v131
	v_cvt_f32_i32_e32 v130, v130
	v_cvt_f32_i32_e32 v139, v139
	v_cvt_f32_i32_e32 v138, v138
	v_cvt_f32_i32_e32 v175, v129
	v_cvt_f32_i32_e32 v174, v128
	v_readlane_b32 s2, v251, 39
	s_lshl_b32 s24, s25, 7
	v_readlane_b32 s3, v251, 40
	s_ashr_i32 s25, s24, 31
	s_lshl_b64 s[24:25], s[24:25], 1
	v_mov_b64_e32 v[128:129], s[2:3]
	v_mad_i64_i32 v[176:177], s[2:3], v162, s54, v[128:129]
	v_lshl_add_u64 v[176:177], v[176:177], 0, s[24:25]
	v_lshl_add_u64 v[176:177], v[176:177], 0, s[8:9]
	v_lshl_add_u64 v[176:177], v[176:177], 0, v[152:153]
	v_cvt_f32_i32_e32 v109, v109
	v_cvt_f32_i32_e32 v108, v108
	v_cvt_f32_i32_e32 v111, v111
	v_cvt_f32_i32_e32 v110, v110
	v_cvt_f32_i32_e32 v101, v101
	v_cvt_f32_i32_e32 v100, v100
	v_cvt_f32_i32_e32 v103, v103
	v_cvt_f32_i32_e32 v102, v102
	v_cvt_f32_i32_e32 v105, v105
	v_cvt_f32_i32_e32 v104, v104
	v_cvt_f32_i32_e32 v99, v99
	v_cvt_f32_i32_e32 v98, v98
	v_cvt_f32_i32_e32 v107, v107
	v_cvt_f32_i32_e32 v106, v106
	v_cvt_f32_i32_e32 v97, v97
	v_cvt_f32_i32_e32 v96, v96
	v_cvt_f32_i32_e32 v93, v93
	v_cvt_f32_i32_e32 v92, v92
	v_cvt_f32_i32_e32 v95, v95
	v_cvt_f32_i32_e32 v94, v94
	v_cvt_f32_i32_e32 v85, v85
	v_cvt_f32_i32_e32 v84, v84
	v_cvt_f32_i32_e32 v87, v87
	v_cvt_f32_i32_e32 v86, v86
	v_cvt_f32_i32_e32 v89, v89
	v_cvt_f32_i32_e32 v88, v88
	v_cvt_f32_i32_e32 v83, v83
	v_cvt_f32_i32_e32 v82, v82
	v_cvt_f32_i32_e32 v91, v91
	v_cvt_f32_i32_e32 v90, v90
	v_cvt_f32_i32_e32 v81, v81
	v_cvt_f32_i32_e32 v80, v80
	v_cvt_f32_i32_e32 v77, v77
	v_cvt_f32_i32_e32 v76, v76
	v_cvt_f32_i32_e32 v79, v79
	v_cvt_f32_i32_e32 v78, v78
	v_cvt_f32_i32_e32 v69, v69
	v_cvt_f32_i32_e32 v68, v68
	v_cvt_f32_i32_e32 v71, v71
	v_cvt_f32_i32_e32 v70, v70
	v_cvt_f32_i32_e32 v73, v73
	v_cvt_f32_i32_e32 v72, v72
	v_cvt_f32_i32_e32 v67, v67
	v_cvt_f32_i32_e32 v66, v66
	v_cvt_f32_i32_e32 v75, v75
	v_cvt_f32_i32_e32 v74, v74
	v_cvt_f32_i32_e32 v65, v65
	v_cvt_f32_i32_e32 v64, v64
	v_cvt_f32_i32_e32 v61, v61
	v_cvt_f32_i32_e32 v60, v60
	s_waitcnt vmcnt(0)
	v_pk_mul_f32 v[178:179], v[112:113], v[172:173] op_sel_hi:[1,0]
	v_pk_mul_f32 v[182:183], v[114:115], v[172:173] op_sel_hi:[1,0]
	v_pk_mul_f32 v[186:187], v[116:117], v[172:173] op_sel_hi:[1,0]
	v_pk_mul_f32 v[192:193], v[118:119], v[172:173] op_sel_hi:[1,0]
	v_pk_mul_f32 v[180:181], v[124:125], v[172:173] op_sel_hi:[1,0]
	v_pk_mul_f32 v[184:185], v[126:127], v[172:173] op_sel_hi:[1,0]
	v_pk_mul_f32 v[188:189], v[120:121], v[172:173] op_sel_hi:[1,0]
	v_pk_mul_f32 v[172:173], v[122:123], v[172:173] op_sel_hi:[1,0]
	v_pk_mul_f32 v[140:141], v[178:179], v[140:141]
	v_pk_mul_f32 v[142:143], v[182:183], v[142:143]
	v_pk_mul_f32 v[132:133], v[186:187], v[132:133]
	v_pk_mul_f32 v[134:135], v[192:193], v[134:135]
	v_pk_mul_f32 v[136:137], v[180:181], v[136:137]
	v_pk_mul_f32 v[130:131], v[172:173], v[130:131]
	v_mul_f32_e32 v163, 0xbfb8aa3b, v140
	v_mul_f32_e32 v171, 0xbfb8aa3b, v141
	v_mul_f32_e32 v172, 0xbfb8aa3b, v142
	v_mul_f32_e32 v173, 0xbfb8aa3b, v143
	v_mul_f32_e32 v178, 0xbfb8aa3b, v132
	v_mul_f32_e32 v179, 0xbfb8aa3b, v133
	v_mul_f32_e32 v180, 0xbfb8aa3b, v134
	v_mul_f32_e32 v181, 0xbfb8aa3b, v135
	v_exp_f32_e32 v163, v163
	v_exp_f32_e32 v171, v171
	v_exp_f32_e32 v172, v172
	v_exp_f32_e32 v173, v173
	v_exp_f32_e32 v178, v178
	v_exp_f32_e32 v179, v179
	v_exp_f32_e32 v180, v180
	v_exp_f32_e32 v181, v181
	v_pk_mul_f32 v[138:139], v[184:185], v[138:139]
	v_add_f32_e32 v163, 1.0, v163
	v_add_f32_e32 v171, 1.0, v171
	v_add_f32_e32 v182, 1.0, v172
	v_add_f32_e32 v183, 1.0, v173
	v_add_f32_e32 v184, 1.0, v178
	v_add_f32_e32 v185, 1.0, v179
	v_add_f32_e32 v186, 1.0, v180
	v_add_f32_e32 v187, 1.0, v181
	v_rcp_f32_e32 v172, v163
	v_rcp_f32_e32 v173, v171
	v_rcp_f32_e32 v178, v182
	v_rcp_f32_e32 v179, v183
	v_rcp_f32_e32 v180, v184
	v_rcp_f32_e32 v181, v185
	v_rcp_f32_e32 v182, v186
	v_rcp_f32_e32 v183, v187
	v_pk_mul_f32 v[174:175], v[188:189], v[174:175]
	v_pk_mul_f32 v[140:141], v[140:141], v[172:173]
	v_pk_mul_f32 v[142:143], v[142:143], v[178:179]
	v_pk_mul_f32 v[132:133], v[132:133], v[180:181]
	v_pk_mul_f32 v[134:135], v[134:135], v[182:183]
	v_pk_mul_f32 v[136:137], v[136:137], v[140:141]
	v_pk_mul_f32 v[138:139], v[138:139], v[142:143]
	v_pk_mul_f32 v[132:133], v[174:175], v[132:133]
	v_pk_mul_f32 v[134:135], v[130:131], v[134:135]
	v_cvt_pk_bf16_f32 v130, v136, v137
	v_cvt_pk_bf16_f32 v131, v138, v139
	v_cvt_pk_bf16_f32 v132, v132, v133
	v_cvt_pk_bf16_f32 v133, v134, v135
	global_store_dwordx4 v[176:177], v[130:133], off
	s_nop 1
	v_mov_b32_e32 v130, v200
	s_waitcnt vmcnt(0)
	v_cvt_f32_i32_e32 v63, v63
	v_or_b32_e32 v131, 16, v162
	v_mad_i64_i32 v[132:133], s[2:3], v131, s54, v[128:129]
	v_lshl_add_u64 v[132:133], v[132:133], 0, s[24:25]
	v_lshl_add_u64 v[132:133], v[132:133], 0, s[8:9]
	v_lshl_add_u64 v[132:133], v[132:133], 0, v[152:153]
	v_cvt_f32_i32_e32 v62, v62
	v_cvt_f32_i32_e32 v53, v53
	v_cvt_f32_i32_e32 v52, v52
	v_cvt_f32_i32_e32 v55, v55
	v_cvt_f32_i32_e32 v54, v54
	v_cvt_f32_i32_e32 v57, v57
	v_cvt_f32_i32_e32 v56, v56
	v_cvt_f32_i32_e32 v51, v51
	v_cvt_f32_i32_e32 v50, v50
	v_cvt_f32_i32_e32 v59, v59
	v_cvt_f32_i32_e32 v58, v58
	v_cvt_f32_i32_e32 v49, v49
	v_cvt_f32_i32_e32 v48, v48
	v_cvt_f32_i32_e32 v45, v45
	v_cvt_f32_i32_e32 v44, v44
	v_cvt_f32_i32_e32 v47, v47
	v_cvt_f32_i32_e32 v46, v46
	v_cvt_f32_i32_e32 v37, v37
	v_cvt_f32_i32_e32 v36, v36
	v_cvt_f32_i32_e32 v39, v39
	v_cvt_f32_i32_e32 v38, v38
	v_cvt_f32_i32_e32 v41, v41
	v_cvt_f32_i32_e32 v40, v40
	v_cvt_f32_i32_e32 v35, v35
	v_cvt_f32_i32_e32 v34, v34
	v_cvt_f32_i32_e32 v43, v43
	v_cvt_f32_i32_e32 v42, v42
	v_cvt_f32_i32_e32 v33, v33
	v_cvt_f32_i32_e32 v32, v32
	v_cvt_f32_i32_e32 v29, v29
	v_cvt_f32_i32_e32 v28, v28
	v_cvt_f32_i32_e32 v31, v31
	v_cvt_f32_i32_e32 v30, v30
	v_cvt_f32_i32_e32 v21, v21
	v_cvt_f32_i32_e32 v20, v20
	v_cvt_f32_i32_e32 v23, v23
	v_cvt_f32_i32_e32 v22, v22
	v_cvt_f32_i32_e32 v25, v25
	v_cvt_f32_i32_e32 v24, v24
	v_cvt_f32_i32_e32 v19, v19
	v_cvt_f32_i32_e32 v18, v18
	v_cvt_f32_i32_e32 v27, v27
	v_cvt_f32_i32_e32 v26, v26
	v_cvt_f32_i32_e32 v17, v17
	v_cvt_f32_i32_e32 v16, v16
	v_cvt_f32_i32_e32 v13, v13
	v_cvt_f32_i32_e32 v12, v12
	v_cvt_f32_i32_e32 v15, v15
	v_cvt_f32_i32_e32 v14, v14
	v_cvt_f32_i32_e32 v5, v5
	v_cvt_f32_i32_e32 v4, v4
	v_cvt_f32_i32_e32 v7, v7
	v_cvt_f32_i32_e32 v6, v6
	v_cvt_f32_i32_e32 v9, v9
	v_cvt_f32_i32_e32 v8, v8
	v_cvt_f32_i32_e32 v3, v3
	v_cvt_f32_i32_e32 v2, v2
	v_cvt_f32_i32_e32 v11, v11
	v_cvt_f32_i32_e32 v10, v10
	v_cvt_f32_i32_e32 v1, v1
	v_cvt_f32_i32_e32 v0, v0
	s_andn2_b64 vcc, exec, s[0:1]
	s_mov_b64 s[0:1], -1
	v_readlane_b32 s65, v251, 9
	v_readlane_b32 s66, v251, 10
	v_readlane_b32 s67, v251, 11
	v_readlane_b32 s68, v251, 12
	v_readlane_b32 s69, v251, 13
	v_pk_mul_f32 v[134:135], v[112:113], v[130:131] op_sel_hi:[1,0]
	v_pk_mul_f32 v[138:139], v[114:115], v[130:131] op_sel_hi:[1,0]
	v_pk_mul_f32 v[142:143], v[116:117], v[130:131] op_sel_hi:[1,0]
	v_pk_mul_f32 v[174:175], v[118:119], v[130:131] op_sel_hi:[1,0]
	v_pk_mul_f32 v[136:137], v[124:125], v[130:131] op_sel_hi:[1,0]
	v_pk_mul_f32 v[140:141], v[126:127], v[130:131] op_sel_hi:[1,0]
	v_pk_mul_f32 v[172:173], v[120:121], v[130:131] op_sel_hi:[1,0]
	v_pk_mul_f32 v[130:131], v[122:123], v[130:131] op_sel_hi:[1,0]
	v_pk_mul_f32 v[108:109], v[134:135], v[108:109]
	v_pk_mul_f32 v[110:111], v[138:139], v[110:111]
	v_pk_mul_f32 v[100:101], v[142:143], v[100:101]
	v_pk_mul_f32 v[102:103], v[174:175], v[102:103]
	v_pk_mul_f32 v[104:105], v[136:137], v[104:105]
	v_pk_mul_f32 v[98:99], v[130:131], v[98:99]
	v_mul_f32_e32 v130, 0xbfb8aa3b, v108
	v_mul_f32_e32 v131, 0xbfb8aa3b, v109
	v_mul_f32_e32 v134, 0xbfb8aa3b, v110
	v_mul_f32_e32 v135, 0xbfb8aa3b, v111
	v_mul_f32_e32 v136, 0xbfb8aa3b, v100
	v_mul_f32_e32 v137, 0xbfb8aa3b, v101
	v_mul_f32_e32 v138, 0xbfb8aa3b, v102
	v_mul_f32_e32 v139, 0xbfb8aa3b, v103
	v_exp_f32_e32 v130, v130
	v_exp_f32_e32 v131, v131
	v_exp_f32_e32 v134, v134
	v_exp_f32_e32 v135, v135
	v_exp_f32_e32 v136, v136
	v_exp_f32_e32 v137, v137
	v_exp_f32_e32 v138, v138
	v_exp_f32_e32 v139, v139
	v_add_f32_e32 v130, 1.0, v130
	v_add_f32_e32 v131, 1.0, v131
	v_add_f32_e32 v134, 1.0, v134
	v_add_f32_e32 v135, 1.0, v135
	v_add_f32_e32 v136, 1.0, v136
	v_add_f32_e32 v137, 1.0, v137
	v_add_f32_e32 v138, 1.0, v138
	v_add_f32_e32 v139, 1.0, v139
	v_rcp_f32_e32 v130, v130
	v_rcp_f32_e32 v131, v131
	v_rcp_f32_e32 v134, v134
	v_rcp_f32_e32 v135, v135
	v_rcp_f32_e32 v136, v136
	v_rcp_f32_e32 v137, v137
	v_rcp_f32_e32 v138, v138
	v_rcp_f32_e32 v139, v139
	v_pk_mul_f32 v[106:107], v[140:141], v[106:107]
	v_pk_mul_f32 v[96:97], v[172:173], v[96:97]
	v_pk_mul_f32 v[108:109], v[108:109], v[130:131]
	v_pk_mul_f32 v[110:111], v[110:111], v[134:135]
	v_pk_mul_f32 v[100:101], v[100:101], v[136:137]
	v_pk_mul_f32 v[102:103], v[102:103], v[138:139]
	v_pk_mul_f32 v[104:105], v[104:105], v[108:109]
	v_pk_mul_f32 v[106:107], v[106:107], v[110:111]
	v_pk_mul_f32 v[100:101], v[96:97], v[100:101]
	v_pk_mul_f32 v[102:103], v[98:99], v[102:103]
	v_cvt_pk_bf16_f32 v96, v104, v105
	v_cvt_pk_bf16_f32 v97, v106, v107
	v_cvt_pk_bf16_f32 v98, v100, v101
	v_cvt_pk_bf16_f32 v99, v102, v103
	global_store_dwordx4 v[132:133], v[96:99], off
	s_nop 1
	v_mov_b32_e32 v96, v201
	s_waitcnt vmcnt(0)
	s_nop 0
	v_or_b32_e32 v97, 32, v162
	v_mad_i64_i32 v[98:99], s[2:3], v97, s54, v[128:129]
	v_lshl_add_u64 v[98:99], v[98:99], 0, s[24:25]
	v_lshl_add_u64 v[98:99], v[98:99], 0, s[8:9]
	v_lshl_add_u64 v[98:99], v[98:99], 0, v[152:153]
	v_pk_mul_f32 v[100:101], v[112:113], v[96:97] op_sel_hi:[1,0]
	v_pk_mul_f32 v[104:105], v[114:115], v[96:97] op_sel_hi:[1,0]
	v_pk_mul_f32 v[108:109], v[116:117], v[96:97] op_sel_hi:[1,0]
	v_pk_mul_f32 v[130:131], v[118:119], v[96:97] op_sel_hi:[1,0]
	v_pk_mul_f32 v[102:103], v[124:125], v[96:97] op_sel_hi:[1,0]
	v_pk_mul_f32 v[106:107], v[126:127], v[96:97] op_sel_hi:[1,0]
	v_pk_mul_f32 v[110:111], v[120:121], v[96:97] op_sel_hi:[1,0]
	v_pk_mul_f32 v[96:97], v[122:123], v[96:97] op_sel_hi:[1,0]
	v_pk_mul_f32 v[92:93], v[100:101], v[92:93]
	v_pk_mul_f32 v[94:95], v[104:105], v[94:95]
	v_pk_mul_f32 v[84:85], v[108:109], v[84:85]
	v_pk_mul_f32 v[86:87], v[130:131], v[86:87]
	v_pk_mul_f32 v[88:89], v[102:103], v[88:89]
	v_pk_mul_f32 v[82:83], v[96:97], v[82:83]
	v_mul_f32_e32 v96, 0xbfb8aa3b, v92
	v_mul_f32_e32 v97, 0xbfb8aa3b, v93
	v_mul_f32_e32 v100, 0xbfb8aa3b, v94
	v_mul_f32_e32 v101, 0xbfb8aa3b, v95
	v_mul_f32_e32 v102, 0xbfb8aa3b, v84
	v_mul_f32_e32 v103, 0xbfb8aa3b, v85
	v_mul_f32_e32 v104, 0xbfb8aa3b, v86
	v_mul_f32_e32 v105, 0xbfb8aa3b, v87
	v_exp_f32_e32 v96, v96
	v_exp_f32_e32 v97, v97
	v_exp_f32_e32 v100, v100
	v_exp_f32_e32 v101, v101
	v_exp_f32_e32 v102, v102
	v_exp_f32_e32 v103, v103
	v_exp_f32_e32 v104, v104
	v_exp_f32_e32 v105, v105
	v_add_f32_e32 v96, 1.0, v96
	v_add_f32_e32 v97, 1.0, v97
	v_add_f32_e32 v100, 1.0, v100
	v_add_f32_e32 v101, 1.0, v101
	v_add_f32_e32 v102, 1.0, v102
	v_add_f32_e32 v103, 1.0, v103
	v_add_f32_e32 v104, 1.0, v104
	v_add_f32_e32 v105, 1.0, v105
	v_rcp_f32_e32 v96, v96
	v_rcp_f32_e32 v97, v97
	v_rcp_f32_e32 v100, v100
	v_rcp_f32_e32 v101, v101
	v_rcp_f32_e32 v102, v102
	v_rcp_f32_e32 v103, v103
	v_rcp_f32_e32 v104, v104
	v_rcp_f32_e32 v105, v105
	v_pk_mul_f32 v[90:91], v[106:107], v[90:91]
	v_pk_mul_f32 v[80:81], v[110:111], v[80:81]
	v_pk_mul_f32 v[92:93], v[92:93], v[96:97]
	v_pk_mul_f32 v[94:95], v[94:95], v[100:101]
	v_pk_mul_f32 v[84:85], v[84:85], v[102:103]
	v_pk_mul_f32 v[86:87], v[86:87], v[104:105]
	v_pk_mul_f32 v[88:89], v[88:89], v[92:93]
	v_pk_mul_f32 v[90:91], v[90:91], v[94:95]
	v_pk_mul_f32 v[84:85], v[80:81], v[84:85]
	v_pk_mul_f32 v[86:87], v[82:83], v[86:87]
	v_cvt_pk_bf16_f32 v80, v88, v89
	v_cvt_pk_bf16_f32 v81, v90, v91
	v_cvt_pk_bf16_f32 v82, v84, v85
	v_cvt_pk_bf16_f32 v83, v86, v87
	global_store_dwordx4 v[98:99], v[80:83], off
	s_nop 1
	v_mov_b32_e32 v80, v202
	s_waitcnt vmcnt(0)
	s_nop 0
	v_or_b32_e32 v81, 48, v162
	v_mad_i64_i32 v[82:83], s[2:3], v81, s54, v[128:129]
	v_lshl_add_u64 v[82:83], v[82:83], 0, s[24:25]
	v_lshl_add_u64 v[82:83], v[82:83], 0, s[8:9]
	v_lshl_add_u64 v[82:83], v[82:83], 0, v[152:153]
	v_pk_mul_f32 v[84:85], v[112:113], v[80:81] op_sel_hi:[1,0]
	v_pk_mul_f32 v[88:89], v[114:115], v[80:81] op_sel_hi:[1,0]
	v_pk_mul_f32 v[92:93], v[116:117], v[80:81] op_sel_hi:[1,0]
	v_pk_mul_f32 v[96:97], v[118:119], v[80:81] op_sel_hi:[1,0]
	v_pk_mul_f32 v[86:87], v[124:125], v[80:81] op_sel_hi:[1,0]
	v_pk_mul_f32 v[90:91], v[126:127], v[80:81] op_sel_hi:[1,0]
	v_pk_mul_f32 v[94:95], v[120:121], v[80:81] op_sel_hi:[1,0]
	v_pk_mul_f32 v[80:81], v[122:123], v[80:81] op_sel_hi:[1,0]
	v_pk_mul_f32 v[76:77], v[84:85], v[76:77]
	v_pk_mul_f32 v[78:79], v[88:89], v[78:79]
	v_pk_mul_f32 v[68:69], v[92:93], v[68:69]
	v_pk_mul_f32 v[70:71], v[96:97], v[70:71]
	v_pk_mul_f32 v[72:73], v[86:87], v[72:73]
	v_pk_mul_f32 v[66:67], v[80:81], v[66:67]
	v_mul_f32_e32 v80, 0xbfb8aa3b, v76
	v_mul_f32_e32 v81, 0xbfb8aa3b, v77
	v_mul_f32_e32 v84, 0xbfb8aa3b, v78
	v_mul_f32_e32 v85, 0xbfb8aa3b, v79
	v_mul_f32_e32 v86, 0xbfb8aa3b, v68
	v_mul_f32_e32 v87, 0xbfb8aa3b, v69
	v_mul_f32_e32 v88, 0xbfb8aa3b, v70
	v_mul_f32_e32 v89, 0xbfb8aa3b, v71
	v_exp_f32_e32 v80, v80
	v_exp_f32_e32 v81, v81
	v_exp_f32_e32 v84, v84
	v_exp_f32_e32 v85, v85
	v_exp_f32_e32 v86, v86
	v_exp_f32_e32 v87, v87
	v_exp_f32_e32 v88, v88
	v_exp_f32_e32 v89, v89
	v_add_f32_e32 v80, 1.0, v80
	v_add_f32_e32 v81, 1.0, v81
	v_add_f32_e32 v84, 1.0, v84
	v_add_f32_e32 v85, 1.0, v85
	v_add_f32_e32 v86, 1.0, v86
	v_add_f32_e32 v87, 1.0, v87
	v_add_f32_e32 v88, 1.0, v88
	v_add_f32_e32 v89, 1.0, v89
	v_rcp_f32_e32 v80, v80
	v_rcp_f32_e32 v81, v81
	v_rcp_f32_e32 v84, v84
	v_rcp_f32_e32 v85, v85
	v_rcp_f32_e32 v86, v86
	v_rcp_f32_e32 v87, v87
	v_rcp_f32_e32 v88, v88
	v_rcp_f32_e32 v89, v89
	v_pk_mul_f32 v[74:75], v[90:91], v[74:75]
	v_pk_mul_f32 v[64:65], v[94:95], v[64:65]
	v_pk_mul_f32 v[76:77], v[76:77], v[80:81]
	v_pk_mul_f32 v[78:79], v[78:79], v[84:85]
	v_pk_mul_f32 v[68:69], v[68:69], v[86:87]
	v_pk_mul_f32 v[70:71], v[70:71], v[88:89]
	v_pk_mul_f32 v[72:73], v[72:73], v[76:77]
	v_pk_mul_f32 v[74:75], v[74:75], v[78:79]
	v_pk_mul_f32 v[68:69], v[64:65], v[68:69]
	v_pk_mul_f32 v[70:71], v[66:67], v[70:71]
	v_cvt_pk_bf16_f32 v64, v72, v73
	v_cvt_pk_bf16_f32 v65, v74, v75
	v_cvt_pk_bf16_f32 v66, v68, v69
	v_cvt_pk_bf16_f32 v67, v70, v71
	global_store_dwordx4 v[82:83], v[64:67], off
	s_nop 1
	v_mov_b32_e32 v64, v203
	s_waitcnt vmcnt(0)
	s_nop 0
	v_add_u32_e32 v65, 0x80, v162
	v_mad_i64_i32 v[66:67], s[2:3], v65, s54, v[128:129]
	v_lshl_add_u64 v[66:67], v[66:67], 0, s[24:25]
	v_lshl_add_u64 v[66:67], v[66:67], 0, s[8:9]
	v_lshl_add_u64 v[66:67], v[66:67], 0, v[152:153]
	v_pk_mul_f32 v[68:69], v[112:113], v[64:65] op_sel_hi:[1,0]
	v_pk_mul_f32 v[72:73], v[114:115], v[64:65] op_sel_hi:[1,0]
	v_pk_mul_f32 v[76:77], v[116:117], v[64:65] op_sel_hi:[1,0]
	v_pk_mul_f32 v[80:81], v[118:119], v[64:65] op_sel_hi:[1,0]
	v_pk_mul_f32 v[70:71], v[124:125], v[64:65] op_sel_hi:[1,0]
	v_pk_mul_f32 v[74:75], v[126:127], v[64:65] op_sel_hi:[1,0]
	v_pk_mul_f32 v[78:79], v[120:121], v[64:65] op_sel_hi:[1,0]
	v_pk_mul_f32 v[64:65], v[122:123], v[64:65] op_sel_hi:[1,0]
	v_pk_mul_f32 v[60:61], v[68:69], v[60:61]
	v_pk_mul_f32 v[62:63], v[72:73], v[62:63]
	v_pk_mul_f32 v[52:53], v[76:77], v[52:53]
	v_pk_mul_f32 v[54:55], v[80:81], v[54:55]
	v_pk_mul_f32 v[56:57], v[70:71], v[56:57]
	v_pk_mul_f32 v[50:51], v[64:65], v[50:51]
	v_mul_f32_e32 v64, 0xbfb8aa3b, v60
	v_mul_f32_e32 v65, 0xbfb8aa3b, v61
	v_mul_f32_e32 v68, 0xbfb8aa3b, v62
	v_mul_f32_e32 v69, 0xbfb8aa3b, v63
	v_mul_f32_e32 v70, 0xbfb8aa3b, v52
	v_mul_f32_e32 v71, 0xbfb8aa3b, v53
	v_mul_f32_e32 v72, 0xbfb8aa3b, v54
	v_mul_f32_e32 v73, 0xbfb8aa3b, v55
	v_exp_f32_e32 v64, v64
	v_exp_f32_e32 v65, v65
	v_exp_f32_e32 v68, v68
	v_exp_f32_e32 v69, v69
	v_exp_f32_e32 v70, v70
	v_exp_f32_e32 v71, v71
	v_exp_f32_e32 v72, v72
	v_exp_f32_e32 v73, v73
	v_add_f32_e32 v64, 1.0, v64
	v_add_f32_e32 v65, 1.0, v65
	v_add_f32_e32 v68, 1.0, v68
	v_add_f32_e32 v69, 1.0, v69
	v_add_f32_e32 v70, 1.0, v70
	v_add_f32_e32 v71, 1.0, v71
	v_add_f32_e32 v72, 1.0, v72
	v_add_f32_e32 v73, 1.0, v73
	v_rcp_f32_e32 v64, v64
	v_rcp_f32_e32 v65, v65
	v_rcp_f32_e32 v68, v68
	v_rcp_f32_e32 v69, v69
	v_rcp_f32_e32 v70, v70
	v_rcp_f32_e32 v71, v71
	v_rcp_f32_e32 v72, v72
	v_rcp_f32_e32 v73, v73
	v_pk_mul_f32 v[58:59], v[74:75], v[58:59]
	v_pk_mul_f32 v[48:49], v[78:79], v[48:49]
	v_pk_mul_f32 v[60:61], v[60:61], v[64:65]
	v_pk_mul_f32 v[62:63], v[62:63], v[68:69]
	v_pk_mul_f32 v[52:53], v[52:53], v[70:71]
	v_pk_mul_f32 v[54:55], v[54:55], v[72:73]
	v_pk_mul_f32 v[56:57], v[56:57], v[60:61]
	v_pk_mul_f32 v[58:59], v[58:59], v[62:63]
	v_pk_mul_f32 v[52:53], v[48:49], v[52:53]
	v_pk_mul_f32 v[54:55], v[50:51], v[54:55]
	v_cvt_pk_bf16_f32 v48, v56, v57
	v_cvt_pk_bf16_f32 v49, v58, v59
	v_cvt_pk_bf16_f32 v50, v52, v53
	v_cvt_pk_bf16_f32 v51, v54, v55
	global_store_dwordx4 v[66:67], v[48:51], off
	s_nop 1
	v_mov_b32_e32 v48, v204
	s_waitcnt vmcnt(0)
	s_nop 0
	v_add_u32_e32 v49, 0x90, v162
	v_mad_i64_i32 v[50:51], s[2:3], v49, s54, v[128:129]
	v_lshl_add_u64 v[50:51], v[50:51], 0, s[24:25]
	v_lshl_add_u64 v[50:51], v[50:51], 0, s[8:9]
	v_lshl_add_u64 v[50:51], v[50:51], 0, v[152:153]
	v_pk_mul_f32 v[52:53], v[112:113], v[48:49] op_sel_hi:[1,0]
	v_pk_mul_f32 v[56:57], v[114:115], v[48:49] op_sel_hi:[1,0]
	v_pk_mul_f32 v[60:61], v[116:117], v[48:49] op_sel_hi:[1,0]
	v_pk_mul_f32 v[64:65], v[118:119], v[48:49] op_sel_hi:[1,0]
	v_pk_mul_f32 v[54:55], v[124:125], v[48:49] op_sel_hi:[1,0]
	v_pk_mul_f32 v[58:59], v[126:127], v[48:49] op_sel_hi:[1,0]
	v_pk_mul_f32 v[62:63], v[120:121], v[48:49] op_sel_hi:[1,0]
	v_pk_mul_f32 v[48:49], v[122:123], v[48:49] op_sel_hi:[1,0]
	v_pk_mul_f32 v[44:45], v[52:53], v[44:45]
	v_pk_mul_f32 v[46:47], v[56:57], v[46:47]
	v_pk_mul_f32 v[36:37], v[60:61], v[36:37]
	v_pk_mul_f32 v[38:39], v[64:65], v[38:39]
	v_pk_mul_f32 v[40:41], v[54:55], v[40:41]
	v_pk_mul_f32 v[34:35], v[48:49], v[34:35]
	v_mul_f32_e32 v48, 0xbfb8aa3b, v44
	v_mul_f32_e32 v49, 0xbfb8aa3b, v45
	v_mul_f32_e32 v52, 0xbfb8aa3b, v46
	v_mul_f32_e32 v53, 0xbfb8aa3b, v47
	v_mul_f32_e32 v54, 0xbfb8aa3b, v36
	v_mul_f32_e32 v55, 0xbfb8aa3b, v37
	v_mul_f32_e32 v56, 0xbfb8aa3b, v38
	v_mul_f32_e32 v57, 0xbfb8aa3b, v39
	v_exp_f32_e32 v48, v48
	v_exp_f32_e32 v49, v49
	v_exp_f32_e32 v52, v52
	v_exp_f32_e32 v53, v53
	v_exp_f32_e32 v54, v54
	v_exp_f32_e32 v55, v55
	v_exp_f32_e32 v56, v56
	v_exp_f32_e32 v57, v57
	v_add_f32_e32 v48, 1.0, v48
	v_add_f32_e32 v49, 1.0, v49
	v_add_f32_e32 v52, 1.0, v52
	v_add_f32_e32 v53, 1.0, v53
	v_add_f32_e32 v54, 1.0, v54
	v_add_f32_e32 v55, 1.0, v55
	v_add_f32_e32 v56, 1.0, v56
	v_add_f32_e32 v57, 1.0, v57
	v_rcp_f32_e32 v48, v48
	v_rcp_f32_e32 v49, v49
	v_rcp_f32_e32 v52, v52
	v_rcp_f32_e32 v53, v53
	v_rcp_f32_e32 v54, v54
	v_rcp_f32_e32 v55, v55
	v_rcp_f32_e32 v56, v56
	v_rcp_f32_e32 v57, v57
	v_pk_mul_f32 v[42:43], v[58:59], v[42:43]
	v_pk_mul_f32 v[32:33], v[62:63], v[32:33]
	v_pk_mul_f32 v[44:45], v[44:45], v[48:49]
	v_pk_mul_f32 v[46:47], v[46:47], v[52:53]
	v_pk_mul_f32 v[36:37], v[36:37], v[54:55]
	v_pk_mul_f32 v[38:39], v[38:39], v[56:57]
	v_pk_mul_f32 v[40:41], v[40:41], v[44:45]
	v_pk_mul_f32 v[42:43], v[42:43], v[46:47]
	v_pk_mul_f32 v[36:37], v[32:33], v[36:37]
	v_pk_mul_f32 v[38:39], v[34:35], v[38:39]
	v_cvt_pk_bf16_f32 v32, v40, v41
	v_cvt_pk_bf16_f32 v33, v42, v43
	v_cvt_pk_bf16_f32 v34, v36, v37
	v_cvt_pk_bf16_f32 v35, v38, v39
	global_store_dwordx4 v[50:51], v[32:35], off
	s_nop 1
	v_mov_b32_e32 v32, v205
	s_waitcnt vmcnt(0)
	s_nop 0
	v_add_u32_e32 v33, 0xa0, v162
	v_mad_i64_i32 v[34:35], s[2:3], v33, s54, v[128:129]
	v_lshl_add_u64 v[34:35], v[34:35], 0, s[24:25]
	v_lshl_add_u64 v[34:35], v[34:35], 0, s[8:9]
	v_lshl_add_u64 v[34:35], v[34:35], 0, v[152:153]
	v_pk_mul_f32 v[36:37], v[112:113], v[32:33] op_sel_hi:[1,0]
	v_pk_mul_f32 v[40:41], v[114:115], v[32:33] op_sel_hi:[1,0]
	v_pk_mul_f32 v[44:45], v[116:117], v[32:33] op_sel_hi:[1,0]
	v_pk_mul_f32 v[48:49], v[118:119], v[32:33] op_sel_hi:[1,0]
	v_pk_mul_f32 v[38:39], v[124:125], v[32:33] op_sel_hi:[1,0]
	v_pk_mul_f32 v[42:43], v[126:127], v[32:33] op_sel_hi:[1,0]
	v_pk_mul_f32 v[46:47], v[120:121], v[32:33] op_sel_hi:[1,0]
	v_pk_mul_f32 v[32:33], v[122:123], v[32:33] op_sel_hi:[1,0]
	v_pk_mul_f32 v[28:29], v[36:37], v[28:29]
	v_pk_mul_f32 v[30:31], v[40:41], v[30:31]
	v_pk_mul_f32 v[20:21], v[44:45], v[20:21]
	v_pk_mul_f32 v[22:23], v[48:49], v[22:23]
	v_pk_mul_f32 v[24:25], v[38:39], v[24:25]
	v_pk_mul_f32 v[18:19], v[32:33], v[18:19]
	v_mul_f32_e32 v32, 0xbfb8aa3b, v28
	v_mul_f32_e32 v33, 0xbfb8aa3b, v29
	v_mul_f32_e32 v36, 0xbfb8aa3b, v30
	v_mul_f32_e32 v37, 0xbfb8aa3b, v31
	v_mul_f32_e32 v38, 0xbfb8aa3b, v20
	v_mul_f32_e32 v39, 0xbfb8aa3b, v21
	v_mul_f32_e32 v40, 0xbfb8aa3b, v22
	v_mul_f32_e32 v41, 0xbfb8aa3b, v23
	v_exp_f32_e32 v32, v32
	v_exp_f32_e32 v33, v33
	v_exp_f32_e32 v36, v36
	v_exp_f32_e32 v37, v37
	v_exp_f32_e32 v38, v38
	v_exp_f32_e32 v39, v39
	v_exp_f32_e32 v40, v40
	v_exp_f32_e32 v41, v41
	v_add_f32_e32 v32, 1.0, v32
	v_add_f32_e32 v33, 1.0, v33
	v_add_f32_e32 v36, 1.0, v36
	v_add_f32_e32 v37, 1.0, v37
	v_add_f32_e32 v38, 1.0, v38
	v_add_f32_e32 v39, 1.0, v39
	v_add_f32_e32 v40, 1.0, v40
	v_add_f32_e32 v41, 1.0, v41
	v_rcp_f32_e32 v32, v32
	v_rcp_f32_e32 v33, v33
	v_rcp_f32_e32 v36, v36
	v_rcp_f32_e32 v37, v37
	v_rcp_f32_e32 v38, v38
	v_rcp_f32_e32 v39, v39
	v_rcp_f32_e32 v40, v40
	v_rcp_f32_e32 v41, v41
	v_pk_mul_f32 v[26:27], v[42:43], v[26:27]
	v_pk_mul_f32 v[16:17], v[46:47], v[16:17]
	v_pk_mul_f32 v[28:29], v[28:29], v[32:33]
	v_pk_mul_f32 v[30:31], v[30:31], v[36:37]
	v_pk_mul_f32 v[20:21], v[20:21], v[38:39]
	v_pk_mul_f32 v[22:23], v[22:23], v[40:41]
	v_pk_mul_f32 v[24:25], v[24:25], v[28:29]
	v_pk_mul_f32 v[26:27], v[26:27], v[30:31]
	v_pk_mul_f32 v[20:21], v[16:17], v[20:21]
	v_pk_mul_f32 v[22:23], v[18:19], v[22:23]
	v_cvt_pk_bf16_f32 v16, v24, v25
	v_cvt_pk_bf16_f32 v17, v26, v27
	v_cvt_pk_bf16_f32 v18, v20, v21
	v_cvt_pk_bf16_f32 v19, v22, v23
	global_store_dwordx4 v[34:35], v[16:19], off
	s_nop 1
	v_mov_b32_e32 v16, v206
	s_waitcnt vmcnt(0)
	s_nop 0
	v_add_u32_e32 v17, 0xb0, v162
	v_mad_i64_i32 v[18:19], s[2:3], v17, s54, v[128:129]
	v_lshl_add_u64 v[18:19], v[18:19], 0, s[24:25]
	v_lshl_add_u64 v[18:19], v[18:19], 0, s[8:9]
	v_lshl_add_u64 v[18:19], v[18:19], 0, v[152:153]
	v_pk_mul_f32 v[20:21], v[112:113], v[16:17] op_sel_hi:[1,0]
	v_pk_mul_f32 v[24:25], v[114:115], v[16:17] op_sel_hi:[1,0]
	v_pk_mul_f32 v[28:29], v[116:117], v[16:17] op_sel_hi:[1,0]
	v_pk_mul_f32 v[32:33], v[118:119], v[16:17] op_sel_hi:[1,0]
	v_pk_mul_f32 v[22:23], v[124:125], v[16:17] op_sel_hi:[1,0]
	v_pk_mul_f32 v[26:27], v[126:127], v[16:17] op_sel_hi:[1,0]
	v_pk_mul_f32 v[30:31], v[120:121], v[16:17] op_sel_hi:[1,0]
	v_pk_mul_f32 v[16:17], v[122:123], v[16:17] op_sel_hi:[1,0]
	v_pk_mul_f32 v[12:13], v[20:21], v[12:13]
	v_pk_mul_f32 v[14:15], v[24:25], v[14:15]
	v_pk_mul_f32 v[4:5], v[28:29], v[4:5]
	v_pk_mul_f32 v[6:7], v[32:33], v[6:7]
	v_pk_mul_f32 v[8:9], v[22:23], v[8:9]
	v_pk_mul_f32 v[2:3], v[16:17], v[2:3]
	v_mul_f32_e32 v16, 0xbfb8aa3b, v12
	v_mul_f32_e32 v17, 0xbfb8aa3b, v13
	v_mul_f32_e32 v20, 0xbfb8aa3b, v14
	v_mul_f32_e32 v21, 0xbfb8aa3b, v15
	v_mul_f32_e32 v22, 0xbfb8aa3b, v4
	v_mul_f32_e32 v23, 0xbfb8aa3b, v5
	v_mul_f32_e32 v24, 0xbfb8aa3b, v6
	v_mul_f32_e32 v25, 0xbfb8aa3b, v7
	v_exp_f32_e32 v16, v16
	v_exp_f32_e32 v17, v17
	v_exp_f32_e32 v20, v20
	v_exp_f32_e32 v21, v21
	v_exp_f32_e32 v22, v22
	v_exp_f32_e32 v23, v23
	v_exp_f32_e32 v24, v24
	v_exp_f32_e32 v25, v25
	v_add_f32_e32 v16, 1.0, v16
	v_add_f32_e32 v17, 1.0, v17
	v_add_f32_e32 v20, 1.0, v20
	v_add_f32_e32 v21, 1.0, v21
	v_add_f32_e32 v22, 1.0, v22
	v_add_f32_e32 v23, 1.0, v23
	v_add_f32_e32 v24, 1.0, v24
	v_add_f32_e32 v25, 1.0, v25
	v_rcp_f32_e32 v16, v16
	v_rcp_f32_e32 v17, v17
	v_rcp_f32_e32 v20, v20
	v_rcp_f32_e32 v21, v21
	v_rcp_f32_e32 v22, v22
	v_rcp_f32_e32 v23, v23
	v_rcp_f32_e32 v24, v24
	v_rcp_f32_e32 v25, v25
	v_pk_mul_f32 v[10:11], v[26:27], v[10:11]
	v_pk_mul_f32 v[0:1], v[30:31], v[0:1]
	v_pk_mul_f32 v[12:13], v[12:13], v[16:17]
	v_pk_mul_f32 v[14:15], v[14:15], v[20:21]
	v_pk_mul_f32 v[4:5], v[4:5], v[22:23]
	v_pk_mul_f32 v[6:7], v[6:7], v[24:25]
	v_pk_mul_f32 v[8:9], v[8:9], v[12:13]
	v_pk_mul_f32 v[10:11], v[10:11], v[14:15]
	v_pk_mul_f32 v[4:5], v[0:1], v[4:5]
	v_pk_mul_f32 v[6:7], v[2:3], v[6:7]
	v_cvt_pk_bf16_f32 v0, v8, v9
	v_cvt_pk_bf16_f32 v1, v10, v11
	v_cvt_pk_bf16_f32 v2, v4, v5
	v_cvt_pk_bf16_f32 v3, v6, v7
	global_store_dwordx4 v[18:19], v[0:3], off
	s_cbranch_vccnz .LBB0_361
	s_andn2_b64 vcc, exec, s[10:11]
	s_cbranch_vccnz .LBB0_360
	s_barrier
	s_branch .LBB0_360

.LBB0_1039:
	v_lshl_add_u32 v168, s12, 8, v172
	v_lshl_or_b32 v176, s13, 8, v174
	v_readlane_b32 s2, v252, 26
	v_ashrrev_i32_e32 v169, 31, v168
	v_ashrrev_i32_e32 v177, 31, v176
	v_readlane_b32 s3, v252, 27
	v_lshl_add_u64 v[170:171], v[168:169], 2, s[8:9]
	v_cvt_f32_i32_e32 v186, v92
	v_lshl_add_u64 v[178:179], v[176:177], 2, s[2:3]
	global_load_dword v169, v[170:171], off
	global_load_dword v210, v[170:171], off offset:64
	global_load_dword v211, v[170:171], off offset:128
	global_load_dword v212, v[170:171], off offset:192
	global_load_dword v213, v[170:171], off offset:512
	global_load_dword v214, v[170:171], off offset:576
	global_load_dword v215, v[170:171], off offset:640
	global_load_dword v216, v[170:171], off offset:704
	global_load_dwordx4 v[100:103], v[178:179], off
	global_load_dwordx4 v[88:91], v[178:179], off offset:16
	global_load_dwordx4 v[76:79], v[178:179], off offset:512
	v_cvt_f32_i32_e32 v187, v93
	v_cvt_f32_i32_e32 v188, v94
	v_cvt_f32_i32_e32 v189, v95
	global_load_dwordx4 v[92:95], v[178:179], off offset:528
	v_cvt_f32_i32_e32 v180, v136
	v_cvt_f32_i32_e32 v181, v137
	v_cvt_f32_i32_e32 v138, v138
	v_cvt_f32_i32_e32 v139, v139
	v_cvt_f32_i32_e32 v182, v132
	v_cvt_f32_i32_e32 v183, v133
	v_cvt_f32_i32_e32 v184, v134
	v_cvt_f32_i32_e32 v185, v135
	v_mov_b64_e32 v[132:133], s[36:37]
	s_movk_i32 s12, 0x3000
	v_mad_i64_i32 v[136:137], s[2:3], v168, s12, v[132:133]
	v_lshlrev_b64 v[134:135], 1, v[176:177]
	v_lshl_add_u64 v[176:177], v[136:137], 0, v[134:135]
	v_cvt_f32_i32_e32 v128, v128
	v_cvt_f32_i32_e32 v129, v129
	v_cvt_f32_i32_e32 v130, v130
	v_cvt_f32_i32_e32 v120, v120
	v_cvt_f32_i32_e32 v122, v122
	v_cvt_f32_i32_e32 v124, v124
	v_cvt_f32_i32_e32 v125, v125
	v_cvt_f32_i32_e32 v126, v126
	v_cvt_f32_i32_e32 v127, v127
	v_cvt_f32_i32_e32 v121, v121
	v_cvt_f32_i32_e32 v123, v123
	v_cvt_f32_i32_e32 v116, v116
	v_cvt_f32_i32_e32 v117, v117
	v_cvt_f32_i32_e32 v118, v118
	v_cvt_f32_i32_e32 v119, v119
	v_cvt_f32_i32_e32 v112, v112
	v_cvt_f32_i32_e32 v113, v113
	v_cvt_f32_i32_e32 v114, v114
	v_cvt_f32_i32_e32 v109, v109
	v_cvt_f32_i32_e32 v110, v110
	v_cvt_f32_i32_e32 v111, v111
	v_cvt_f32_i32_e32 v104, v104
	v_cvt_f32_i32_e32 v105, v105
	v_cvt_f32_i32_e32 v106, v106
	v_cvt_f32_i32_e32 v108, v108
	v_cvt_f32_i32_e32 v96, v96
	v_cvt_f32_i32_e32 v97, v97
	v_cvt_f32_i32_e32 v98, v98
	v_cvt_f32_i32_e32 v99, v99
	v_cvt_f32_i32_e32 v84, v84
	v_cvt_f32_i32_e32 v85, v85
	v_cvt_f32_i32_e32 v86, v86
	v_cvt_f32_i32_e32 v80, v80
	v_cvt_f32_i32_e32 v81, v81
	v_cvt_f32_i32_e32 v82, v82
	v_cvt_f32_i32_e32 v83, v83
	v_cvt_f32_i32_e32 v72, v72
	v_cvt_f32_i32_e32 v73, v73
	v_cvt_f32_i32_e32 v74, v74
	v_cvt_f32_i32_e32 v68, v68
	v_cvt_f32_i32_e32 v69, v69
	v_cvt_f32_i32_e32 v70, v70
	v_cvt_f32_i32_e32 v71, v71
	v_cvt_f32_i32_e32 v64, v64
	v_cvt_f32_i32_e32 v65, v65
	v_cvt_f32_i32_e32 v66, v66
	v_cvt_f32_i32_e32 v60, v60
	v_cvt_f32_i32_e32 v61, v61
	v_cvt_f32_i32_e32 v62, v62
	v_cvt_f32_i32_e32 v63, v63
	v_cvt_f32_i32_e32 v56, v56
	v_cvt_f32_i32_e32 v57, v57
	v_cvt_f32_i32_e32 v58, v58
	v_cvt_f32_i32_e32 v52, v52
	v_cvt_f32_i32_e32 v53, v53
	v_cvt_f32_i32_e32 v54, v54
	v_cvt_f32_i32_e32 v55, v55
	v_cvt_f32_i32_e32 v48, v48
	v_cvt_f32_i32_e32 v49, v49
	s_waitcnt vmcnt(0)
	v_mul_f32_e32 v136, v100, v169
	v_mul_f32_e32 v137, v101, v169
	v_mul_f32_e32 v178, v102, v169
	v_mul_f32_e32 v179, v103, v169
	v_mul_f32_e32 v200, v88, v169
	v_mul_f32_e32 v201, v89, v169
	v_mul_f32_e32 v202, v90, v169
	v_mul_f32_e32 v203, v91, v169
	v_mul_f32_e32 v136, v136, v180
	v_mul_f32_e32 v137, v137, v181
	v_mul_f32_e32 v138, v178, v138
	v_mul_f32_e32 v139, v179, v139
	v_mul_f32_e32 v178, v200, v182
	v_mul_f32_e32 v179, v201, v183
	v_mul_f32_e32 v180, v202, v184
	v_mul_f32_e32 v181, v203, v185
	v_mul_f32_e32 v136, 0xbfb8aa3b, v136
	v_mul_f32_e32 v137, 0xbfb8aa3b, v137
	v_mul_f32_e32 v138, 0xbfb8aa3b, v138
	v_mul_f32_e32 v139, 0xbfb8aa3b, v139
	v_mul_f32_e32 v178, 0xbfb8aa3b, v178
	v_mul_f32_e32 v179, 0xbfb8aa3b, v179
	v_mul_f32_e32 v180, 0xbfb8aa3b, v180
	v_mul_f32_e32 v181, 0xbfb8aa3b, v181
	v_exp_f32_e32 v136, v136
	v_exp_f32_e32 v137, v137
	v_exp_f32_e32 v138, v138
	v_exp_f32_e32 v139, v139
	v_exp_f32_e32 v178, v178
	v_exp_f32_e32 v179, v179
	v_exp_f32_e32 v180, v180
	v_exp_f32_e32 v181, v181
	v_add_f32_e32 v136, 1.0, v136
	v_add_f32_e32 v137, 1.0, v137
	v_add_f32_e32 v138, 1.0, v138
	v_add_f32_e32 v139, 1.0, v139
	v_add_f32_e32 v178, 1.0, v178
	v_add_f32_e32 v179, 1.0, v179
	v_add_f32_e32 v180, 1.0, v180
	v_add_f32_e32 v181, 1.0, v181
	v_rcp_f32_e32 v136, v136
	v_rcp_f32_e32 v137, v137
	v_rcp_f32_e32 v138, v138
	v_rcp_f32_e32 v139, v139
	v_rcp_f32_e32 v178, v178
	v_rcp_f32_e32 v179, v179
	v_rcp_f32_e32 v180, v180
	v_rcp_f32_e32 v181, v181
	v_cvt_pk_bf16_f32 v136, v136, v137
	v_cvt_pk_bf16_f32 v137, v138, v139
	v_cvt_pk_bf16_f32 v138, v178, v179
	v_cvt_pk_bf16_f32 v139, v180, v181
	global_store_dwordx4 v[176:177], v[136:139], off
	v_mul_f32_e32 v204, v76, v169
	v_mul_f32_e32 v205, v77, v169
	v_mul_f32_e32 v138, v92, v169
	v_mul_f32_e32 v128, v138, v128
	v_mul_f32_e32 v138, v93, v169
	v_mul_f32_e32 v128, 0xbfb8aa3b, v128
	v_mul_f32_e32 v129, v138, v129
	v_exp_f32_e32 v128, v128
	v_mul_f32_e32 v129, 0xbfb8aa3b, v129
	v_exp_f32_e32 v129, v129
	v_mul_f32_e32 v206, v78, v169
	v_add_f32_e32 v128, 1.0, v128
	v_rcp_f32_e32 v138, v128
	v_add_f32_e32 v128, 1.0, v129
	v_mul_f32_e32 v129, v94, v169
	v_mul_f32_e32 v129, v129, v130
	v_cvt_f32_i32_e32 v130, v131
	v_mul_f32_e32 v136, v79, v169
	v_mul_f32_e32 v131, v95, v169
	v_mul_f32_e32 v182, v204, v186
	v_mul_f32_e32 v183, v205, v187
	v_mul_f32_e32 v184, v206, v188
	v_mul_f32_e32 v136, v136, v189
	v_mul_f32_e32 v129, 0xbfb8aa3b, v129
	v_mul_f32_e32 v130, v131, v130
	v_mul_f32_e32 v182, 0xbfb8aa3b, v182
	v_mul_f32_e32 v183, 0xbfb8aa3b, v183
	v_mul_f32_e32 v184, 0xbfb8aa3b, v184
	v_mul_f32_e32 v136, 0xbfb8aa3b, v136
	v_exp_f32_e32 v129, v129
	v_mul_f32_e32 v130, 0xbfb8aa3b, v130
	v_exp_f32_e32 v182, v182
	v_exp_f32_e32 v183, v183
	v_exp_f32_e32 v184, v184
	v_exp_f32_e32 v136, v136
	v_exp_f32_e32 v130, v130
	v_rcp_f32_e32 v131, v128
	v_add_f32_e32 v128, 1.0, v129
	v_add_f32_e32 v182, 1.0, v182
	v_add_f32_e32 v183, 1.0, v183
	v_add_f32_e32 v137, 1.0, v184
	v_add_f32_e32 v136, 1.0, v136
	v_rcp_f32_e32 v139, v128
	v_add_f32_e32 v128, 1.0, v130
	v_rcp_f32_e32 v182, v182
	v_rcp_f32_e32 v183, v183
	v_rcp_f32_e32 v137, v137
	v_rcp_f32_e32 v136, v136
	v_rcp_f32_e32 v169, v128
	v_cvt_pk_bf16_f32 v128, v182, v183
	v_cvt_pk_bf16_f32 v130, v138, v131
	v_cvt_pk_bf16_f32 v129, v137, v136
	v_cvt_pk_bf16_f32 v131, v139, v169
	global_store_dwordx4 v[176:177], v[128:131], off offset:256
	s_nop 1
	v_mov_b32_e32 v128, v210
	s_waitcnt vmcnt(0)
	v_cvt_f32_i32_e32 v50, v50
	v_or_b32_e32 v129, 16, v168
	v_cvt_f32_i32_e32 v44, v44
	v_cvt_f32_i32_e32 v45, v45
	v_cvt_f32_i32_e32 v46, v46
	v_cvt_f32_i32_e32 v47, v47
	v_cvt_f32_i32_e32 v40, v40
	v_cvt_f32_i32_e32 v41, v41
	v_cvt_f32_i32_e32 v42, v42
	v_cvt_f32_i32_e32 v36, v36
	v_cvt_f32_i32_e32 v37, v37
	v_cvt_f32_i32_e32 v38, v38
	v_cvt_f32_i32_e32 v39, v39
	v_cvt_f32_i32_e32 v32, v32
	v_cvt_f32_i32_e32 v33, v33
	v_cvt_f32_i32_e32 v34, v34
	v_cvt_f32_i32_e32 v28, v28
	v_cvt_f32_i32_e32 v29, v29
	v_cvt_f32_i32_e32 v30, v30
	v_cvt_f32_i32_e32 v31, v31
	v_cvt_f32_i32_e32 v24, v24
	v_cvt_f32_i32_e32 v25, v25
	v_cvt_f32_i32_e32 v26, v26
	v_cvt_f32_i32_e32 v20, v20
	v_cvt_f32_i32_e32 v21, v21
	v_cvt_f32_i32_e32 v22, v22
	v_cvt_f32_i32_e32 v23, v23
	v_cvt_f32_i32_e32 v16, v16
	v_cvt_f32_i32_e32 v17, v17
	v_cvt_f32_i32_e32 v18, v18
	v_cvt_f32_i32_e32 v12, v12
	v_cvt_f32_i32_e32 v13, v13
	v_cvt_f32_i32_e32 v14, v14
	v_cvt_f32_i32_e32 v15, v15
	v_cvt_f32_i32_e32 v8, v8
	v_cvt_f32_i32_e32 v9, v9
	v_cvt_f32_i32_e32 v10, v10
	v_cvt_f32_i32_e32 v4, v4
	v_cvt_f32_i32_e32 v5, v5
	v_cvt_f32_i32_e32 v6, v6
	v_cvt_f32_i32_e32 v7, v7
	v_cvt_f32_i32_e32 v0, v0
	v_cvt_f32_i32_e32 v1, v1
	v_cvt_f32_i32_e32 v2, v2
	s_andn2_b64 vcc, exec, s[0:1]
	s_mov_b64 s[0:1], -1
	v_mul_f32_e32 v138, v88, v128
	v_mul_f32_e32 v120, v138, v120
	v_mul_f32_e32 v120, 0xbfb8aa3b, v120
	v_exp_f32_e32 v120, v120
	v_mul_f32_e32 v169, v90, v128
	v_mul_f32_e32 v122, v169, v122
	v_mul_f32_e32 v130, v100, v128
	v_mul_f32_e32 v131, v101, v128
	v_mul_f32_e32 v122, 0xbfb8aa3b, v122
	v_add_f32_e32 v120, 1.0, v120
	v_mul_f32_e32 v136, v102, v128
	v_mul_f32_e32 v137, v103, v128
	v_mul_f32_e32 v139, v89, v128
	v_mul_f32_e32 v124, v130, v124
	v_mul_f32_e32 v125, v131, v125
	v_rcp_f32_e32 v130, v120
	v_exp_f32_e32 v120, v122
	v_mul_f32_e32 v122, v91, v128
	v_mul_f32_e32 v126, v136, v126
	v_mul_f32_e32 v127, v137, v127
	v_mul_f32_e32 v121, v139, v121
	v_mul_f32_e32 v124, 0xbfb8aa3b, v124
	v_mul_f32_e32 v125, 0xbfb8aa3b, v125
	v_mul_f32_e32 v122, v122, v123
	v_mul_f32_e32 v126, 0xbfb8aa3b, v126
	v_mul_f32_e32 v127, 0xbfb8aa3b, v127
	v_mul_f32_e32 v121, 0xbfb8aa3b, v121
	v_exp_f32_e32 v124, v124
	v_exp_f32_e32 v125, v125
	v_mul_f32_e32 v122, 0xbfb8aa3b, v122
	v_exp_f32_e32 v126, v126
	v_exp_f32_e32 v127, v127
	v_exp_f32_e32 v121, v121
	v_exp_f32_e32 v122, v122
	v_add_f32_e32 v124, 1.0, v124
	v_add_f32_e32 v125, 1.0, v125
	v_add_f32_e32 v120, 1.0, v120
	v_add_f32_e32 v126, 1.0, v126
	v_add_f32_e32 v127, 1.0, v127
	v_add_f32_e32 v121, 1.0, v121
	v_rcp_f32_e32 v124, v124
	v_rcp_f32_e32 v125, v125
	v_rcp_f32_e32 v131, v120
	v_add_f32_e32 v120, 1.0, v122
	v_rcp_f32_e32 v126, v126
	v_rcp_f32_e32 v127, v127
	v_rcp_f32_e32 v123, v121
	v_rcp_f32_e32 v136, v120
	v_cvt_pk_bf16_f32 v120, v124, v125
	v_mad_i64_i32 v[124:125], s[2:3], v129, s12, v[132:133]
	v_cvt_pk_bf16_f32 v121, v126, v127
	v_cvt_pk_bf16_f32 v122, v130, v123
	v_cvt_pk_bf16_f32 v123, v131, v136
	v_lshl_add_u64 v[124:125], v[124:125], 0, v[134:135]
	global_store_dwordx4 v[124:125], v[120:123], off
	s_nop 1
	v_mul_f32_e32 v120, v76, v128
	v_mul_f32_e32 v116, v120, v116
	v_mul_f32_e32 v120, v77, v128
	v_mul_f32_e32 v117, v120, v117
	v_mul_f32_e32 v120, v78, v128
	v_mul_f32_e32 v118, v120, v118
	v_mul_f32_e32 v120, v79, v128
	v_mul_f32_e32 v119, v120, v119
	v_mul_f32_e32 v120, v92, v128
	v_mul_f32_e32 v112, v120, v112
	v_mul_f32_e32 v120, v93, v128
	v_mul_f32_e32 v112, 0xbfb8aa3b, v112
	v_mul_f32_e32 v113, v120, v113
	v_exp_f32_e32 v112, v112
	v_mul_f32_e32 v113, 0xbfb8aa3b, v113
	v_exp_f32_e32 v113, v113
	v_mul_f32_e32 v116, 0xbfb8aa3b, v116
	v_add_f32_e32 v112, 1.0, v112
	v_rcp_f32_e32 v120, v112
	v_add_f32_e32 v112, 1.0, v113
	v_mul_f32_e32 v113, v94, v128
	v_mul_f32_e32 v113, v113, v114
	v_cvt_f32_i32_e32 v114, v115
	v_mul_f32_e32 v115, v95, v128
	v_mul_f32_e32 v113, 0xbfb8aa3b, v113
	v_mul_f32_e32 v117, 0xbfb8aa3b, v117
	v_mul_f32_e32 v114, v115, v114
	v_mul_f32_e32 v118, 0xbfb8aa3b, v118
	v_mul_f32_e32 v119, 0xbfb8aa3b, v119
	v_exp_f32_e32 v113, v113
	v_mul_f32_e32 v114, 0xbfb8aa3b, v114
	v_exp_f32_e32 v116, v116
	v_exp_f32_e32 v117, v117
	v_exp_f32_e32 v118, v118
	v_exp_f32_e32 v119, v119
	v_exp_f32_e32 v114, v114
	v_rcp_f32_e32 v115, v112
	v_add_f32_e32 v112, 1.0, v113
	v_add_f32_e32 v116, 1.0, v116
	v_add_f32_e32 v117, 1.0, v117
	v_add_f32_e32 v118, 1.0, v118
	v_add_f32_e32 v119, 1.0, v119
	v_rcp_f32_e32 v121, v112
	v_add_f32_e32 v112, 1.0, v114
	v_rcp_f32_e32 v116, v116
	v_rcp_f32_e32 v117, v117
	v_rcp_f32_e32 v118, v118
	v_rcp_f32_e32 v119, v119
	v_rcp_f32_e32 v122, v112
	v_cvt_pk_bf16_f32 v112, v116, v117
	v_cvt_pk_bf16_f32 v114, v120, v115
	v_cvt_pk_bf16_f32 v113, v118, v119
	v_cvt_pk_bf16_f32 v115, v121, v122
	global_store_dwordx4 v[124:125], v[112:115], off offset:256
	s_nop 1
	v_mov_b32_e32 v112, v211
	s_waitcnt vmcnt(0)
	v_mul_f32_e32 v114, v101, v112
	v_mul_f32_e32 v109, v114, v109
	v_mul_f32_e32 v114, v102, v112
	v_mul_f32_e32 v110, v114, v110
	v_mul_f32_e32 v114, v103, v112
	v_mul_f32_e32 v111, v114, v111
	v_mul_f32_e32 v114, v88, v112
	v_mul_f32_e32 v104, v114, v104
	v_mul_f32_e32 v114, v89, v112
	v_mul_f32_e32 v104, 0xbfb8aa3b, v104
	v_mul_f32_e32 v105, v114, v105
	v_exp_f32_e32 v104, v104
	v_mul_f32_e32 v105, 0xbfb8aa3b, v105
	v_exp_f32_e32 v105, v105
	v_mul_f32_e32 v113, v100, v112
	v_add_f32_e32 v104, 1.0, v104
	v_rcp_f32_e32 v114, v104
	v_add_f32_e32 v104, 1.0, v105
	v_mul_f32_e32 v105, v90, v112
	v_mul_f32_e32 v105, v105, v106
	v_cvt_f32_i32_e32 v106, v107
	v_mul_f32_e32 v108, v113, v108
	v_mul_f32_e32 v107, v91, v112
	v_mul_f32_e32 v108, 0xbfb8aa3b, v108
	v_mul_f32_e32 v109, 0xbfb8aa3b, v109
	v_mul_f32_e32 v105, 0xbfb8aa3b, v105
	v_mul_f32_e32 v106, v107, v106
	v_exp_f32_e32 v108, v108
	v_exp_f32_e32 v109, v109
	v_mul_f32_e32 v110, 0xbfb8aa3b, v110
	v_mul_f32_e32 v111, 0xbfb8aa3b, v111
	v_exp_f32_e32 v105, v105
	v_mul_f32_e32 v106, 0xbfb8aa3b, v106
	v_exp_f32_e32 v110, v110
	v_exp_f32_e32 v111, v111
	v_exp_f32_e32 v106, v106
	v_add_f32_e32 v108, 1.0, v108
	v_add_f32_e32 v109, 1.0, v109
	v_rcp_f32_e32 v107, v104
	v_add_f32_e32 v104, 1.0, v105
	v_rcp_f32_e32 v108, v108
	v_rcp_f32_e32 v109, v109
	v_add_f32_e32 v110, 1.0, v110
	v_add_f32_e32 v111, 1.0, v111
	v_rcp_f32_e32 v115, v104
	v_add_f32_e32 v104, 1.0, v106
	v_rcp_f32_e32 v110, v110
	v_rcp_f32_e32 v111, v111
	v_rcp_f32_e32 v116, v104
	v_or_b32_e32 v113, 32, v168
	v_cvt_pk_bf16_f32 v104, v108, v109
	v_mad_i64_i32 v[108:109], s[2:3], v113, s12, v[132:133]
	v_cvt_pk_bf16_f32 v105, v110, v111
	v_cvt_pk_bf16_f32 v106, v114, v107
	v_cvt_pk_bf16_f32 v107, v115, v116
	v_lshl_add_u64 v[108:109], v[108:109], 0, v[134:135]
	global_store_dwordx4 v[108:109], v[104:107], off
	s_nop 1
	v_mul_f32_e32 v104, v76, v112
	v_mul_f32_e32 v96, v104, v96
	v_mul_f32_e32 v104, v77, v112
	v_mul_f32_e32 v97, v104, v97
	v_mul_f32_e32 v104, v78, v112
	v_mul_f32_e32 v98, v104, v98
	v_mul_f32_e32 v104, v79, v112
	v_mul_f32_e32 v99, v104, v99
	v_mul_f32_e32 v104, v92, v112
	v_mul_f32_e32 v84, v104, v84
	v_mul_f32_e32 v104, v93, v112
	v_mul_f32_e32 v84, 0xbfb8aa3b, v84
	v_mul_f32_e32 v85, v104, v85
	v_exp_f32_e32 v84, v84
	v_mul_f32_e32 v85, 0xbfb8aa3b, v85
	v_exp_f32_e32 v85, v85
	v_mul_f32_e32 v96, 0xbfb8aa3b, v96
	v_add_f32_e32 v84, 1.0, v84
	v_rcp_f32_e32 v104, v84
	v_add_f32_e32 v84, 1.0, v85
	v_mul_f32_e32 v85, v94, v112
	v_mul_f32_e32 v85, v85, v86
	v_cvt_f32_i32_e32 v86, v87
	v_mul_f32_e32 v87, v95, v112
	v_mul_f32_e32 v85, 0xbfb8aa3b, v85
	v_mul_f32_e32 v97, 0xbfb8aa3b, v97
	v_mul_f32_e32 v86, v87, v86
	v_mul_f32_e32 v98, 0xbfb8aa3b, v98
	v_mul_f32_e32 v99, 0xbfb8aa3b, v99
	v_exp_f32_e32 v85, v85
	v_mul_f32_e32 v86, 0xbfb8aa3b, v86
	v_exp_f32_e32 v96, v96
	v_exp_f32_e32 v97, v97
	v_exp_f32_e32 v98, v98
	v_exp_f32_e32 v99, v99
	v_exp_f32_e32 v86, v86
	v_rcp_f32_e32 v87, v84
	v_add_f32_e32 v84, 1.0, v85
	v_add_f32_e32 v96, 1.0, v96
	v_add_f32_e32 v97, 1.0, v97
	v_add_f32_e32 v98, 1.0, v98
	v_add_f32_e32 v99, 1.0, v99
	v_rcp_f32_e32 v105, v84
	v_add_f32_e32 v84, 1.0, v86
	v_rcp_f32_e32 v96, v96
	v_rcp_f32_e32 v97, v97
	v_rcp_f32_e32 v98, v98
	v_rcp_f32_e32 v99, v99
	v_rcp_f32_e32 v106, v84
	v_cvt_pk_bf16_f32 v84, v96, v97
	v_cvt_pk_bf16_f32 v86, v104, v87
	v_cvt_pk_bf16_f32 v85, v98, v99
	v_cvt_pk_bf16_f32 v87, v105, v106
	global_store_dwordx4 v[108:109], v[84:87], off offset:256
	s_nop 1
	v_mov_b32_e32 v84, v212
	s_waitcnt vmcnt(0)
	s_nop 0
	v_or_b32_e32 v85, 48, v168
	v_mul_f32_e32 v86, v100, v84
	v_mul_f32_e32 v80, v86, v80
	v_mul_f32_e32 v86, v101, v84
	v_mul_f32_e32 v81, v86, v81
	v_mul_f32_e32 v86, v102, v84
	v_mul_f32_e32 v82, v86, v82
	v_mul_f32_e32 v86, v103, v84
	v_mul_f32_e32 v83, v86, v83
	v_mul_f32_e32 v86, v88, v84
	v_mul_f32_e32 v72, v86, v72
	v_mul_f32_e32 v86, v89, v84
	v_mul_f32_e32 v72, 0xbfb8aa3b, v72
	v_mul_f32_e32 v73, v86, v73
	v_exp_f32_e32 v72, v72
	v_mul_f32_e32 v73, 0xbfb8aa3b, v73
	v_exp_f32_e32 v73, v73
	v_mul_f32_e32 v80, 0xbfb8aa3b, v80
	v_add_f32_e32 v72, 1.0, v72
	v_rcp_f32_e32 v86, v72
	v_add_f32_e32 v72, 1.0, v73
	v_mul_f32_e32 v73, v90, v84
	v_mul_f32_e32 v73, v73, v74
	v_cvt_f32_i32_e32 v74, v75
	v_mul_f32_e32 v75, v91, v84
	v_mul_f32_e32 v81, 0xbfb8aa3b, v81
	v_mul_f32_e32 v73, 0xbfb8aa3b, v73
	v_mul_f32_e32 v74, v75, v74
	v_exp_f32_e32 v80, v80
	v_exp_f32_e32 v81, v81
	v_mul_f32_e32 v82, 0xbfb8aa3b, v82
	v_mul_f32_e32 v83, 0xbfb8aa3b, v83
	v_exp_f32_e32 v73, v73
	v_mul_f32_e32 v74, 0xbfb8aa3b, v74
	v_exp_f32_e32 v82, v82
	v_exp_f32_e32 v83, v83
	v_exp_f32_e32 v74, v74
	v_add_f32_e32 v80, 1.0, v80
	v_add_f32_e32 v81, 1.0, v81
	v_rcp_f32_e32 v75, v72
	v_add_f32_e32 v72, 1.0, v73
	v_rcp_f32_e32 v80, v80
	v_rcp_f32_e32 v81, v81
	v_add_f32_e32 v82, 1.0, v82
	v_add_f32_e32 v83, 1.0, v83
	v_rcp_f32_e32 v87, v72
	v_add_f32_e32 v72, 1.0, v74
	v_rcp_f32_e32 v82, v82
	v_rcp_f32_e32 v83, v83
	v_rcp_f32_e32 v96, v72
	v_cvt_pk_bf16_f32 v72, v80, v81
	v_mad_i64_i32 v[80:81], s[2:3], v85, s12, v[132:133]
	v_cvt_pk_bf16_f32 v73, v82, v83
	v_cvt_pk_bf16_f32 v74, v86, v75
	v_cvt_pk_bf16_f32 v75, v87, v96
	v_lshl_add_u64 v[80:81], v[80:81], 0, v[134:135]
	global_store_dwordx4 v[80:81], v[72:75], off
	s_nop 1
	v_mul_f32_e32 v72, v76, v84
	v_mul_f32_e32 v68, v72, v68
	v_mul_f32_e32 v72, v77, v84
	v_mul_f32_e32 v69, v72, v69
	v_mul_f32_e32 v72, v78, v84
	v_mul_f32_e32 v70, v72, v70
	v_mul_f32_e32 v72, v79, v84
	v_mul_f32_e32 v71, v72, v71
	v_mul_f32_e32 v72, v92, v84
	v_mul_f32_e32 v64, v72, v64
	v_mul_f32_e32 v72, v93, v84
	v_mul_f32_e32 v64, 0xbfb8aa3b, v64
	v_mul_f32_e32 v65, v72, v65
	v_exp_f32_e32 v64, v64
	v_mul_f32_e32 v65, 0xbfb8aa3b, v65
	v_exp_f32_e32 v65, v65
	v_mul_f32_e32 v68, 0xbfb8aa3b, v68
	v_add_f32_e32 v64, 1.0, v64
	v_rcp_f32_e32 v72, v64
	v_add_f32_e32 v64, 1.0, v65
	v_mul_f32_e32 v65, v94, v84
	v_mul_f32_e32 v65, v65, v66
	v_cvt_f32_i32_e32 v66, v67
	v_mul_f32_e32 v67, v95, v84
	v_mul_f32_e32 v65, 0xbfb8aa3b, v65
	v_mul_f32_e32 v69, 0xbfb8aa3b, v69
	v_mul_f32_e32 v66, v67, v66
	v_mul_f32_e32 v70, 0xbfb8aa3b, v70
	v_mul_f32_e32 v71, 0xbfb8aa3b, v71
	v_exp_f32_e32 v65, v65
	v_mul_f32_e32 v66, 0xbfb8aa3b, v66
	v_exp_f32_e32 v68, v68
	v_exp_f32_e32 v69, v69
	v_exp_f32_e32 v70, v70
	v_exp_f32_e32 v71, v71
	v_exp_f32_e32 v66, v66
	v_rcp_f32_e32 v67, v64
	v_add_f32_e32 v64, 1.0, v65
	v_add_f32_e32 v68, 1.0, v68
	v_add_f32_e32 v69, 1.0, v69
	v_add_f32_e32 v70, 1.0, v70
	v_add_f32_e32 v71, 1.0, v71
	v_rcp_f32_e32 v73, v64
	v_add_f32_e32 v64, 1.0, v66
	v_rcp_f32_e32 v68, v68
	v_rcp_f32_e32 v69, v69
	v_rcp_f32_e32 v70, v70
	v_rcp_f32_e32 v71, v71
	v_rcp_f32_e32 v74, v64
	v_cvt_pk_bf16_f32 v64, v68, v69
	v_cvt_pk_bf16_f32 v66, v72, v67
	v_cvt_pk_bf16_f32 v65, v70, v71
	v_cvt_pk_bf16_f32 v67, v73, v74
	global_store_dwordx4 v[80:81], v[64:67], off offset:256
	s_nop 1
	v_mov_b32_e32 v64, v213
	s_waitcnt vmcnt(0)
	s_nop 0
	v_add_u32_e32 v65, 0x80, v168
	v_mul_f32_e32 v66, v100, v64
	v_mul_f32_e32 v60, v66, v60
	v_mul_f32_e32 v66, v101, v64
	v_mul_f32_e32 v61, v66, v61
	v_mul_f32_e32 v66, v102, v64
	v_mul_f32_e32 v62, v66, v62
	v_mul_f32_e32 v66, v103, v64
	v_mul_f32_e32 v63, v66, v63
	v_mul_f32_e32 v66, v88, v64
	v_mul_f32_e32 v56, v66, v56
	v_mul_f32_e32 v66, v89, v64
	v_mul_f32_e32 v56, 0xbfb8aa3b, v56
	v_mul_f32_e32 v57, v66, v57
	v_exp_f32_e32 v56, v56
	v_mul_f32_e32 v57, 0xbfb8aa3b, v57
	v_exp_f32_e32 v57, v57
	v_mul_f32_e32 v60, 0xbfb8aa3b, v60
	v_add_f32_e32 v56, 1.0, v56
	v_rcp_f32_e32 v66, v56
	v_add_f32_e32 v56, 1.0, v57
	v_mul_f32_e32 v57, v90, v64
	v_mul_f32_e32 v57, v57, v58
	v_cvt_f32_i32_e32 v58, v59
	v_mul_f32_e32 v59, v91, v64
	v_mul_f32_e32 v61, 0xbfb8aa3b, v61
	v_mul_f32_e32 v57, 0xbfb8aa3b, v57
	v_mul_f32_e32 v58, v59, v58
	v_exp_f32_e32 v60, v60
	v_exp_f32_e32 v61, v61
	v_mul_f32_e32 v62, 0xbfb8aa3b, v62
	v_mul_f32_e32 v63, 0xbfb8aa3b, v63
	v_exp_f32_e32 v57, v57
	v_mul_f32_e32 v58, 0xbfb8aa3b, v58
	v_exp_f32_e32 v62, v62
	v_exp_f32_e32 v63, v63
	v_exp_f32_e32 v58, v58
	v_add_f32_e32 v60, 1.0, v60
	v_add_f32_e32 v61, 1.0, v61
	v_rcp_f32_e32 v59, v56
	v_add_f32_e32 v56, 1.0, v57
	v_rcp_f32_e32 v60, v60
	v_rcp_f32_e32 v61, v61
	v_add_f32_e32 v62, 1.0, v62
	v_add_f32_e32 v63, 1.0, v63
	v_rcp_f32_e32 v67, v56
	v_add_f32_e32 v56, 1.0, v58
	v_rcp_f32_e32 v62, v62
	v_rcp_f32_e32 v63, v63
	v_rcp_f32_e32 v68, v56
	v_cvt_pk_bf16_f32 v56, v60, v61
	v_mad_i64_i32 v[60:61], s[2:3], v65, s12, v[132:133]
	v_cvt_pk_bf16_f32 v57, v62, v63
	v_cvt_pk_bf16_f32 v58, v66, v59
	v_cvt_pk_bf16_f32 v59, v67, v68
	v_lshl_add_u64 v[60:61], v[60:61], 0, v[134:135]
	global_store_dwordx4 v[60:61], v[56:59], off
	s_nop 1
	v_mul_f32_e32 v56, v76, v64
	v_mul_f32_e32 v52, v56, v52
	v_mul_f32_e32 v56, v77, v64
	v_mul_f32_e32 v53, v56, v53
	v_mul_f32_e32 v56, v78, v64
	v_mul_f32_e32 v54, v56, v54
	v_mul_f32_e32 v56, v79, v64
	v_mul_f32_e32 v55, v56, v55
	v_mul_f32_e32 v56, v92, v64
	v_mul_f32_e32 v48, v56, v48
	v_mul_f32_e32 v56, v93, v64
	v_mul_f32_e32 v48, 0xbfb8aa3b, v48
	v_mul_f32_e32 v49, v56, v49
	v_exp_f32_e32 v48, v48
	v_mul_f32_e32 v49, 0xbfb8aa3b, v49
	v_exp_f32_e32 v49, v49
	v_mul_f32_e32 v52, 0xbfb8aa3b, v52
	v_add_f32_e32 v48, 1.0, v48
	v_rcp_f32_e32 v56, v48
	v_add_f32_e32 v48, 1.0, v49
	v_mul_f32_e32 v49, v94, v64
	v_mul_f32_e32 v49, v49, v50
	v_cvt_f32_i32_e32 v50, v51
	v_mul_f32_e32 v51, v95, v64
	v_mul_f32_e32 v49, 0xbfb8aa3b, v49
	v_mul_f32_e32 v53, 0xbfb8aa3b, v53
	v_mul_f32_e32 v50, v51, v50
	v_mul_f32_e32 v54, 0xbfb8aa3b, v54
	v_mul_f32_e32 v55, 0xbfb8aa3b, v55
	v_exp_f32_e32 v49, v49
	v_mul_f32_e32 v50, 0xbfb8aa3b, v50
	v_exp_f32_e32 v52, v52
	v_exp_f32_e32 v53, v53
	v_exp_f32_e32 v54, v54
	v_exp_f32_e32 v55, v55
	v_exp_f32_e32 v50, v50
	v_rcp_f32_e32 v51, v48
	v_add_f32_e32 v48, 1.0, v49
	v_add_f32_e32 v52, 1.0, v52
	v_add_f32_e32 v53, 1.0, v53
	v_add_f32_e32 v54, 1.0, v54
	v_add_f32_e32 v55, 1.0, v55
	v_rcp_f32_e32 v57, v48
	v_add_f32_e32 v48, 1.0, v50
	v_rcp_f32_e32 v52, v52
	v_rcp_f32_e32 v53, v53
	v_rcp_f32_e32 v54, v54
	v_rcp_f32_e32 v55, v55
	v_rcp_f32_e32 v58, v48
	v_cvt_pk_bf16_f32 v48, v52, v53
	v_cvt_pk_bf16_f32 v50, v56, v51
	v_cvt_pk_bf16_f32 v49, v54, v55
	v_cvt_pk_bf16_f32 v51, v57, v58
	global_store_dwordx4 v[60:61], v[48:51], off offset:256
	s_nop 1
	v_mov_b32_e32 v48, v214
	s_waitcnt vmcnt(0)
	s_nop 0
	v_add_u32_e32 v49, 0x90, v168
	v_mul_f32_e32 v50, v100, v48
	v_mul_f32_e32 v44, v50, v44
	v_mul_f32_e32 v50, v101, v48
	v_mul_f32_e32 v45, v50, v45
	v_mul_f32_e32 v50, v102, v48
	v_mul_f32_e32 v46, v50, v46
	v_mul_f32_e32 v50, v103, v48
	v_mul_f32_e32 v47, v50, v47
	v_mul_f32_e32 v50, v88, v48
	v_mul_f32_e32 v40, v50, v40
	v_mul_f32_e32 v50, v89, v48
	v_mul_f32_e32 v40, 0xbfb8aa3b, v40
	v_mul_f32_e32 v41, v50, v41
	v_exp_f32_e32 v40, v40
	v_mul_f32_e32 v41, 0xbfb8aa3b, v41
	v_exp_f32_e32 v41, v41
	v_mul_f32_e32 v44, 0xbfb8aa3b, v44
	v_add_f32_e32 v40, 1.0, v40
	v_rcp_f32_e32 v50, v40
	v_add_f32_e32 v40, 1.0, v41
	v_mul_f32_e32 v41, v90, v48
	v_mul_f32_e32 v41, v41, v42
	v_cvt_f32_i32_e32 v42, v43
	v_mul_f32_e32 v43, v91, v48
	v_mul_f32_e32 v45, 0xbfb8aa3b, v45
	v_mul_f32_e32 v41, 0xbfb8aa3b, v41
	v_mul_f32_e32 v42, v43, v42
	v_exp_f32_e32 v44, v44
	v_exp_f32_e32 v45, v45
	v_mul_f32_e32 v46, 0xbfb8aa3b, v46
	v_mul_f32_e32 v47, 0xbfb8aa3b, v47
	v_exp_f32_e32 v41, v41
	v_mul_f32_e32 v42, 0xbfb8aa3b, v42
	v_exp_f32_e32 v46, v46
	v_exp_f32_e32 v47, v47
	v_exp_f32_e32 v42, v42
	v_add_f32_e32 v44, 1.0, v44
	v_add_f32_e32 v45, 1.0, v45
	v_rcp_f32_e32 v43, v40
	v_add_f32_e32 v40, 1.0, v41
	v_rcp_f32_e32 v44, v44
	v_rcp_f32_e32 v45, v45
	v_add_f32_e32 v46, 1.0, v46
	v_add_f32_e32 v47, 1.0, v47
	v_rcp_f32_e32 v51, v40
	v_add_f32_e32 v40, 1.0, v42
	v_rcp_f32_e32 v46, v46
	v_rcp_f32_e32 v47, v47
	v_rcp_f32_e32 v52, v40
	v_cvt_pk_bf16_f32 v40, v44, v45
	v_mad_i64_i32 v[44:45], s[2:3], v49, s12, v[132:133]
	v_cvt_pk_bf16_f32 v41, v46, v47
	v_cvt_pk_bf16_f32 v42, v50, v43
	v_cvt_pk_bf16_f32 v43, v51, v52
	v_lshl_add_u64 v[44:45], v[44:45], 0, v[134:135]
	global_store_dwordx4 v[44:45], v[40:43], off
	s_nop 1
	v_mul_f32_e32 v40, v76, v48
	v_mul_f32_e32 v36, v40, v36
	v_mul_f32_e32 v40, v77, v48
	v_mul_f32_e32 v37, v40, v37
	v_mul_f32_e32 v40, v78, v48
	v_mul_f32_e32 v38, v40, v38
	v_mul_f32_e32 v40, v79, v48
	v_mul_f32_e32 v39, v40, v39
	v_mul_f32_e32 v40, v92, v48
	v_mul_f32_e32 v32, v40, v32
	v_mul_f32_e32 v40, v93, v48
	v_mul_f32_e32 v32, 0xbfb8aa3b, v32
	v_mul_f32_e32 v33, v40, v33
	v_exp_f32_e32 v32, v32
	v_mul_f32_e32 v33, 0xbfb8aa3b, v33
	v_exp_f32_e32 v33, v33
	v_mul_f32_e32 v36, 0xbfb8aa3b, v36
	v_add_f32_e32 v32, 1.0, v32
	v_rcp_f32_e32 v40, v32
	v_add_f32_e32 v32, 1.0, v33
	v_mul_f32_e32 v33, v94, v48
	v_mul_f32_e32 v33, v33, v34
	v_cvt_f32_i32_e32 v34, v35
	v_mul_f32_e32 v35, v95, v48
	v_mul_f32_e32 v33, 0xbfb8aa3b, v33
	v_mul_f32_e32 v37, 0xbfb8aa3b, v37
	v_mul_f32_e32 v34, v35, v34
	v_mul_f32_e32 v38, 0xbfb8aa3b, v38
	v_mul_f32_e32 v39, 0xbfb8aa3b, v39
	v_exp_f32_e32 v33, v33
	v_mul_f32_e32 v34, 0xbfb8aa3b, v34
	v_exp_f32_e32 v36, v36
	v_exp_f32_e32 v37, v37
	v_exp_f32_e32 v38, v38
	v_exp_f32_e32 v39, v39
	v_exp_f32_e32 v34, v34
	v_rcp_f32_e32 v35, v32
	v_add_f32_e32 v32, 1.0, v33
	v_add_f32_e32 v36, 1.0, v36
	v_add_f32_e32 v37, 1.0, v37
	v_add_f32_e32 v38, 1.0, v38
	v_add_f32_e32 v39, 1.0, v39
	v_rcp_f32_e32 v41, v32
	v_add_f32_e32 v32, 1.0, v34
	v_rcp_f32_e32 v36, v36
	v_rcp_f32_e32 v37, v37
	v_rcp_f32_e32 v38, v38
	v_rcp_f32_e32 v39, v39
	v_rcp_f32_e32 v42, v32
	v_cvt_pk_bf16_f32 v32, v36, v37
	v_cvt_pk_bf16_f32 v34, v40, v35
	v_cvt_pk_bf16_f32 v33, v38, v39
	v_cvt_pk_bf16_f32 v35, v41, v42
	global_store_dwordx4 v[44:45], v[32:35], off offset:256
	s_nop 1
	v_mov_b32_e32 v32, v215
	s_waitcnt vmcnt(0)
	s_nop 0
	v_add_u32_e32 v33, 0xa0, v168
	v_mul_f32_e32 v34, v100, v32
	v_mul_f32_e32 v28, v34, v28
	v_mul_f32_e32 v34, v101, v32
	v_mul_f32_e32 v29, v34, v29
	v_mul_f32_e32 v34, v102, v32
	v_mul_f32_e32 v30, v34, v30
	v_mul_f32_e32 v34, v103, v32
	v_mul_f32_e32 v31, v34, v31
	v_mul_f32_e32 v34, v88, v32
	v_mul_f32_e32 v24, v34, v24
	v_mul_f32_e32 v34, v89, v32
	v_mul_f32_e32 v24, 0xbfb8aa3b, v24
	v_mul_f32_e32 v25, v34, v25
	v_exp_f32_e32 v24, v24
	v_mul_f32_e32 v25, 0xbfb8aa3b, v25
	v_exp_f32_e32 v25, v25
	v_mul_f32_e32 v28, 0xbfb8aa3b, v28
	v_add_f32_e32 v24, 1.0, v24
	v_rcp_f32_e32 v34, v24
	v_add_f32_e32 v24, 1.0, v25
	v_mul_f32_e32 v25, v90, v32
	v_mul_f32_e32 v25, v25, v26
	v_cvt_f32_i32_e32 v26, v27
	v_mul_f32_e32 v27, v91, v32
	v_mul_f32_e32 v29, 0xbfb8aa3b, v29
	v_mul_f32_e32 v25, 0xbfb8aa3b, v25
	v_mul_f32_e32 v26, v27, v26
	v_exp_f32_e32 v28, v28
	v_exp_f32_e32 v29, v29
	v_mul_f32_e32 v30, 0xbfb8aa3b, v30
	v_mul_f32_e32 v31, 0xbfb8aa3b, v31
	v_exp_f32_e32 v25, v25
	v_mul_f32_e32 v26, 0xbfb8aa3b, v26
	v_exp_f32_e32 v30, v30
	v_exp_f32_e32 v31, v31
	v_exp_f32_e32 v26, v26
	v_add_f32_e32 v28, 1.0, v28
	v_add_f32_e32 v29, 1.0, v29
	v_rcp_f32_e32 v27, v24
	v_add_f32_e32 v24, 1.0, v25
	v_rcp_f32_e32 v28, v28
	v_rcp_f32_e32 v29, v29
	v_add_f32_e32 v30, 1.0, v30
	v_add_f32_e32 v31, 1.0, v31
	v_rcp_f32_e32 v35, v24
	v_add_f32_e32 v24, 1.0, v26
	v_rcp_f32_e32 v30, v30
	v_rcp_f32_e32 v31, v31
	v_rcp_f32_e32 v36, v24
	v_cvt_pk_bf16_f32 v24, v28, v29
	v_mad_i64_i32 v[28:29], s[2:3], v33, s12, v[132:133]
	v_cvt_pk_bf16_f32 v25, v30, v31
	v_cvt_pk_bf16_f32 v26, v34, v27
	v_cvt_pk_bf16_f32 v27, v35, v36
	v_lshl_add_u64 v[28:29], v[28:29], 0, v[134:135]
	global_store_dwordx4 v[28:29], v[24:27], off
	s_nop 1
	v_mul_f32_e32 v24, v76, v32
	v_mul_f32_e32 v20, v24, v20
	v_mul_f32_e32 v24, v77, v32
	v_mul_f32_e32 v21, v24, v21
	v_mul_f32_e32 v24, v78, v32
	v_mul_f32_e32 v22, v24, v22
	v_mul_f32_e32 v24, v79, v32
	v_mul_f32_e32 v23, v24, v23
	v_mul_f32_e32 v24, v92, v32
	v_mul_f32_e32 v16, v24, v16
	v_mul_f32_e32 v24, v93, v32
	v_mul_f32_e32 v16, 0xbfb8aa3b, v16
	v_mul_f32_e32 v17, v24, v17
	v_exp_f32_e32 v16, v16
	v_mul_f32_e32 v17, 0xbfb8aa3b, v17
	v_exp_f32_e32 v17, v17
	v_mul_f32_e32 v20, 0xbfb8aa3b, v20
	v_add_f32_e32 v16, 1.0, v16
	v_rcp_f32_e32 v24, v16
	v_add_f32_e32 v16, 1.0, v17
	v_mul_f32_e32 v17, v94, v32
	v_mul_f32_e32 v17, v17, v18
	v_cvt_f32_i32_e32 v18, v19
	v_mul_f32_e32 v19, v95, v32
	v_mul_f32_e32 v17, 0xbfb8aa3b, v17
	v_mul_f32_e32 v21, 0xbfb8aa3b, v21
	v_mul_f32_e32 v18, v19, v18
	v_mul_f32_e32 v22, 0xbfb8aa3b, v22
	v_mul_f32_e32 v23, 0xbfb8aa3b, v23
	v_exp_f32_e32 v17, v17
	v_mul_f32_e32 v18, 0xbfb8aa3b, v18
	v_exp_f32_e32 v20, v20
	v_exp_f32_e32 v21, v21
	v_exp_f32_e32 v22, v22
	v_exp_f32_e32 v23, v23
	v_exp_f32_e32 v18, v18
	v_rcp_f32_e32 v19, v16
	v_add_f32_e32 v16, 1.0, v17
	v_add_f32_e32 v20, 1.0, v20
	v_add_f32_e32 v21, 1.0, v21
	v_add_f32_e32 v22, 1.0, v22
	v_add_f32_e32 v23, 1.0, v23
	v_rcp_f32_e32 v25, v16
	v_add_f32_e32 v16, 1.0, v18
	v_rcp_f32_e32 v20, v20
	v_rcp_f32_e32 v21, v21
	v_rcp_f32_e32 v22, v22
	v_rcp_f32_e32 v23, v23
	v_rcp_f32_e32 v26, v16
	v_cvt_pk_bf16_f32 v16, v20, v21
	v_cvt_pk_bf16_f32 v18, v24, v19
	v_cvt_pk_bf16_f32 v17, v22, v23
	v_cvt_pk_bf16_f32 v19, v25, v26
	global_store_dwordx4 v[28:29], v[16:19], off offset:256
	s_nop 1
	v_mov_b32_e32 v16, v216
	s_waitcnt vmcnt(0)
	s_nop 0
	v_add_u32_e32 v17, 0xb0, v168
	v_mul_f32_e32 v18, v100, v16
	v_mul_f32_e32 v12, v18, v12
	v_mul_f32_e32 v18, v101, v16
	v_mul_f32_e32 v13, v18, v13
	v_mul_f32_e32 v18, v102, v16
	v_mul_f32_e32 v14, v18, v14
	v_mul_f32_e32 v18, v103, v16
	v_mul_f32_e32 v15, v18, v15
	v_mul_f32_e32 v18, v88, v16
	v_mul_f32_e32 v8, v18, v8
	v_mul_f32_e32 v18, v89, v16
	v_mul_f32_e32 v8, 0xbfb8aa3b, v8
	v_mul_f32_e32 v9, v18, v9
	v_exp_f32_e32 v8, v8
	v_mul_f32_e32 v9, 0xbfb8aa3b, v9
	v_exp_f32_e32 v9, v9
	v_mul_f32_e32 v12, 0xbfb8aa3b, v12
	v_add_f32_e32 v8, 1.0, v8
	v_rcp_f32_e32 v18, v8
	v_add_f32_e32 v8, 1.0, v9
	v_mul_f32_e32 v9, v90, v16
	v_mul_f32_e32 v9, v9, v10
	v_cvt_f32_i32_e32 v10, v11
	v_mul_f32_e32 v11, v91, v16
	v_mul_f32_e32 v13, 0xbfb8aa3b, v13
	v_mul_f32_e32 v9, 0xbfb8aa3b, v9
	v_mul_f32_e32 v10, v11, v10
	v_exp_f32_e32 v12, v12
	v_exp_f32_e32 v13, v13
	v_mul_f32_e32 v14, 0xbfb8aa3b, v14
	v_mul_f32_e32 v15, 0xbfb8aa3b, v15
	v_exp_f32_e32 v9, v9
	v_mul_f32_e32 v10, 0xbfb8aa3b, v10
	v_exp_f32_e32 v14, v14
	v_exp_f32_e32 v15, v15
	v_exp_f32_e32 v10, v10
	v_add_f32_e32 v12, 1.0, v12
	v_add_f32_e32 v13, 1.0, v13
	v_rcp_f32_e32 v11, v8
	v_add_f32_e32 v8, 1.0, v9
	v_rcp_f32_e32 v12, v12
	v_rcp_f32_e32 v13, v13
	v_add_f32_e32 v14, 1.0, v14
	v_add_f32_e32 v15, 1.0, v15
	v_rcp_f32_e32 v19, v8
	v_add_f32_e32 v8, 1.0, v10
	v_rcp_f32_e32 v14, v14
	v_rcp_f32_e32 v15, v15
	v_rcp_f32_e32 v20, v8
	v_cvt_pk_bf16_f32 v8, v12, v13
	v_mad_i64_i32 v[12:13], s[2:3], v17, s12, v[132:133]
	v_cvt_pk_bf16_f32 v9, v14, v15
	v_cvt_pk_bf16_f32 v10, v18, v11
	v_cvt_pk_bf16_f32 v11, v19, v20
	v_lshl_add_u64 v[12:13], v[12:13], 0, v[134:135]
	global_store_dwordx4 v[12:13], v[8:11], off
	s_nop 1
	v_mul_f32_e32 v8, v76, v16
	v_mul_f32_e32 v4, v8, v4
	v_mul_f32_e32 v8, v77, v16
	v_mul_f32_e32 v5, v8, v5
	v_mul_f32_e32 v8, v78, v16
	v_mul_f32_e32 v6, v8, v6
	v_mul_f32_e32 v8, v79, v16
	v_mul_f32_e32 v7, v8, v7
	v_mul_f32_e32 v8, v92, v16
	v_mul_f32_e32 v0, v8, v0
	v_mul_f32_e32 v8, v93, v16
	v_mul_f32_e32 v0, 0xbfb8aa3b, v0
	v_mul_f32_e32 v1, v8, v1
	v_exp_f32_e32 v0, v0
	v_mul_f32_e32 v1, 0xbfb8aa3b, v1
	v_exp_f32_e32 v1, v1
	v_mul_f32_e32 v4, 0xbfb8aa3b, v4
	v_add_f32_e32 v0, 1.0, v0
	v_rcp_f32_e32 v8, v0
	v_add_f32_e32 v0, 1.0, v1
	v_mul_f32_e32 v1, v94, v16
	v_mul_f32_e32 v1, v1, v2
	v_cvt_f32_i32_e32 v2, v3
	v_mul_f32_e32 v3, v95, v16
	v_mul_f32_e32 v1, 0xbfb8aa3b, v1
	v_mul_f32_e32 v5, 0xbfb8aa3b, v5
	v_mul_f32_e32 v2, v3, v2
	v_mul_f32_e32 v6, 0xbfb8aa3b, v6
	v_mul_f32_e32 v7, 0xbfb8aa3b, v7
	v_exp_f32_e32 v1, v1
	v_mul_f32_e32 v2, 0xbfb8aa3b, v2
	v_exp_f32_e32 v4, v4
	v_exp_f32_e32 v5, v5
	v_exp_f32_e32 v6, v6
	v_exp_f32_e32 v7, v7
	v_exp_f32_e32 v2, v2
	v_rcp_f32_e32 v3, v0
	v_add_f32_e32 v0, 1.0, v1
	v_add_f32_e32 v4, 1.0, v4
	v_add_f32_e32 v5, 1.0, v5
	v_add_f32_e32 v6, 1.0, v6
	v_add_f32_e32 v7, 1.0, v7
	v_rcp_f32_e32 v9, v0
	v_add_f32_e32 v0, 1.0, v2
	v_rcp_f32_e32 v4, v4
	v_rcp_f32_e32 v5, v5
	v_rcp_f32_e32 v6, v6
	v_rcp_f32_e32 v7, v7
	v_rcp_f32_e32 v10, v0
	v_cvt_pk_bf16_f32 v0, v4, v5
	v_cvt_pk_bf16_f32 v2, v8, v3
	v_cvt_pk_bf16_f32 v1, v6, v7
	v_cvt_pk_bf16_f32 v3, v9, v10
	global_store_dwordx4 v[12:13], v[0:3], off offset:256
	s_cbranch_vccnz .LBB0_1031
	s_andn2_b64 vcc, exec, s[6:7]
	s_cbranch_vccnz .LBB0_1030
	s_barrier
	s_branch .LBB0_1030

.LBB0_1970:
	v_lshl_or_b32 v48, s23, 8, v176
	v_readlane_b32 s24, v254, 0
	v_lshl_add_u32 v166, s22, 8, v174
	v_readlane_b32 s44, v251, 8
	v_ashrrev_i32_e32 v49, 31, v48
	v_readlane_b32 s25, v254, 1
	v_ashrrev_i32_e32 v167, 31, v166
	v_readlane_b32 s50, v251, 14
	v_readlane_b32 s51, v251, 15
	v_lshl_add_u64 v[56:57], v[48:49], 2, s[24:25]
	global_load_dwordx4 v[52:55], v[56:57], off offset:16
	global_load_dwordx4 v[60:63], v[56:57], off
	global_load_dwordx4 v[48:51], v[56:57], off offset:528
	s_nop 0
	global_load_dwordx4 v[56:59], v[56:57], off offset:512
	v_lshl_add_u64 v[168:169], v[166:167], 2, s[50:51]
	global_load_dword v170, v[168:169], off
	global_load_dword v200, v[168:169], off offset:64
	global_load_dword v201, v[168:169], off offset:128
	global_load_dword v202, v[168:169], off offset:192
	global_load_dword v203, v[168:169], off offset:512
	global_load_dword v204, v[168:169], off offset:576
	global_load_dword v205, v[168:169], off offset:640
	global_load_dword v206, v[168:169], off offset:704
	v_cvt_f32_i32_e32 v141, v141
	v_cvt_f32_i32_e32 v140, v140
	v_cvt_f32_i32_e32 v137, v137
	v_cvt_f32_i32_e32 v136, v136
	v_cvt_f32_i32_e32 v139, v139
	v_cvt_f32_i32_e32 v138, v138
	v_cvt_f32_i32_e32 v133, v133
	v_cvt_f32_i32_e32 v132, v132
	v_cvt_f32_i32_e32 v129, v129
	v_cvt_f32_i32_e32 v128, v128
	v_cvt_f32_i32_e32 v131, v131
	v_cvt_f32_i32_e32 v130, v130
	v_readlane_b32 s24, v251, 39
	s_lshl_b32 s22, s23, 7
	v_readlane_b32 s25, v251, 40
	s_ashr_i32 s23, s22, 31
	s_lshl_b64 s[22:23], s[22:23], 1
	v_cvt_f32_i32_e32 v125, v125
	v_cvt_f32_i32_e32 v124, v124
	v_cvt_f32_i32_e32 v121, v121
	v_cvt_f32_i32_e32 v120, v120
	v_cvt_f32_i32_e32 v123, v123
	v_cvt_f32_i32_e32 v122, v122
	v_cvt_f32_i32_e32 v117, v117
	v_cvt_f32_i32_e32 v116, v116
	v_cvt_f32_i32_e32 v113, v113
	v_cvt_f32_i32_e32 v112, v112
	v_cvt_f32_i32_e32 v115, v115
	v_cvt_f32_i32_e32 v114, v114
	v_cvt_f32_i32_e32 v109, v109
	v_cvt_f32_i32_e32 v108, v108
	v_cvt_f32_i32_e32 v105, v105
	v_cvt_f32_i32_e32 v104, v104
	v_cvt_f32_i32_e32 v107, v107
	v_cvt_f32_i32_e32 v106, v106
	v_cvt_f32_i32_e32 v101, v101
	v_cvt_f32_i32_e32 v100, v100
	v_cvt_f32_i32_e32 v97, v97
	v_cvt_f32_i32_e32 v96, v96
	v_cvt_f32_i32_e32 v99, v99
	v_cvt_f32_i32_e32 v98, v98
	v_cvt_f32_i32_e32 v93, v93
	v_cvt_f32_i32_e32 v92, v92
	v_cvt_f32_i32_e32 v89, v89
	v_cvt_f32_i32_e32 v88, v88
	v_cvt_f32_i32_e32 v91, v91
	v_cvt_f32_i32_e32 v90, v90
	v_cvt_f32_i32_e32 v85, v85
	v_cvt_f32_i32_e32 v84, v84
	v_cvt_f32_i32_e32 v81, v81
	v_cvt_f32_i32_e32 v80, v80
	v_cvt_f32_i32_e32 v83, v83
	v_cvt_f32_i32_e32 v82, v82
	v_cvt_f32_i32_e32 v77, v77
	v_cvt_f32_i32_e32 v76, v76
	v_cvt_f32_i32_e32 v73, v73
	v_cvt_f32_i32_e32 v72, v72
	v_cvt_f32_i32_e32 v75, v75
	v_cvt_f32_i32_e32 v74, v74
	v_cvt_f32_i32_e32 v69, v69
	v_cvt_f32_i32_e32 v68, v68
	v_cvt_f32_i32_e32 v65, v65
	v_cvt_f32_i32_e32 v64, v64
	v_cvt_f32_i32_e32 v67, v67
	v_cvt_f32_i32_e32 v66, v66
	v_cvt_f32_i32_e32 v45, v45
	v_cvt_f32_i32_e32 v44, v44
	v_cvt_f32_i32_e32 v41, v41
	v_cvt_f32_i32_e32 v40, v40
	v_cvt_f32_i32_e32 v43, v43
	v_cvt_f32_i32_e32 v42, v42
	v_cvt_f32_i32_e32 v37, v37
	v_cvt_f32_i32_e32 v36, v36
	v_cvt_f32_i32_e32 v33, v33
	v_cvt_f32_i32_e32 v32, v32
	v_cvt_f32_i32_e32 v35, v35
	v_cvt_f32_i32_e32 v34, v34
	v_cvt_f32_i32_e32 v29, v29
	v_cvt_f32_i32_e32 v28, v28
	s_waitcnt vmcnt(0)
	v_pk_mul_f32 v[178:179], v[60:61], v[170:171] op_sel_hi:[1,0]
	v_cvt_f32_i32_e32 v25, v25
	v_pk_mul_f32 v[140:141], v[178:179], v[140:141]
	v_cvt_f32_i32_e32 v24, v24
	v_mul_f32_e32 v167, 0xbfb8aa3b, v140
	v_exp_f32_e32 v167, v167
	v_cvt_f32_i32_e32 v27, v27
	v_cvt_f32_i32_e32 v26, v26
	v_cvt_f32_i32_e32 v21, v21
	v_add_f32_e32 v167, 1.0, v167
	v_rcp_f32_e32 v178, v167
	v_mul_f32_e32 v167, 0xbfb8aa3b, v141
	v_exp_f32_e32 v167, v167
	v_cvt_f32_i32_e32 v20, v20
	v_cvt_f32_i32_e32 v17, v17
	v_cvt_f32_i32_e32 v16, v16
	v_add_f32_e32 v167, 1.0, v167
	v_rcp_f32_e32 v179, v167
	v_cvt_f32_i32_e32 v19, v19
	v_cvt_f32_i32_e32 v18, v18
	v_cvt_f32_i32_e32 v13, v13
	v_pk_mul_f32 v[140:141], v[140:141], v[178:179]
	v_pk_mul_f32 v[178:179], v[56:57], v[170:171] op_sel_hi:[1,0]
	v_cvt_f32_i32_e32 v12, v12
	v_pk_mul_f32 v[136:137], v[178:179], v[136:137]
	v_cvt_f32_i32_e32 v9, v9
	v_pk_mul_f32 v[136:137], v[136:137], v[140:141]
	v_cvt_f32_i32_e32 v141, v143
	v_cvt_f32_i32_e32 v140, v142
	v_pk_mul_f32 v[142:143], v[62:63], v[170:171] op_sel_hi:[1,0]
	v_cvt_f32_i32_e32 v8, v8
	v_cvt_f32_i32_e32 v11, v11
	v_pk_mul_f32 v[140:141], v[142:143], v[140:141]
	v_cvt_f32_i32_e32 v10, v10
	v_mul_f32_e32 v142, 0xbfb8aa3b, v140
	v_mul_f32_e32 v143, 0xbfb8aa3b, v141
	v_exp_f32_e32 v142, v142
	v_exp_f32_e32 v143, v143
	v_cvt_f32_i32_e32 v5, v5
	v_cvt_f32_i32_e32 v4, v4
	v_add_f32_e32 v142, 1.0, v142
	v_add_f32_e32 v143, 1.0, v143
	v_rcp_f32_e32 v142, v142
	v_rcp_f32_e32 v143, v143
	v_cvt_f32_i32_e32 v1, v1
	v_cvt_f32_i32_e32 v0, v0
	v_cvt_f32_i32_e32 v3, v3
	v_pk_mul_f32 v[140:141], v[140:141], v[142:143]
	v_pk_mul_f32 v[142:143], v[58:59], v[170:171] op_sel_hi:[1,0]
	v_cvt_f32_i32_e32 v2, v2
	v_pk_mul_f32 v[138:139], v[142:143], v[138:139]
	s_andn2_b64 vcc, exec, s[42:43]
	v_pk_mul_f32 v[138:139], v[138:139], v[140:141]
	v_pk_mul_f32 v[140:141], v[52:53], v[170:171] op_sel_hi:[1,0]
	v_readlane_b32 s45, v251, 9
	v_pk_mul_f32 v[132:133], v[140:141], v[132:133]
	v_readlane_b32 s46, v251, 10
	v_mul_f32_e32 v140, 0xbfb8aa3b, v132
	v_mul_f32_e32 v141, 0xbfb8aa3b, v133
	v_exp_f32_e32 v140, v140
	v_exp_f32_e32 v141, v141
	v_readlane_b32 s47, v251, 11
	v_readlane_b32 s48, v251, 12
	v_add_f32_e32 v140, 1.0, v140
	v_add_f32_e32 v141, 1.0, v141
	v_rcp_f32_e32 v140, v140
	v_rcp_f32_e32 v141, v141
	v_readlane_b32 s49, v251, 13
	v_pk_mul_f32 v[132:133], v[132:133], v[140:141]
	v_pk_mul_f32 v[140:141], v[48:49], v[170:171] op_sel_hi:[1,0]
	s_nop 0
	v_pk_mul_f32 v[128:129], v[140:141], v[128:129]
	s_nop 0
	v_pk_mul_f32 v[128:129], v[128:129], v[132:133]
	v_cvt_f32_i32_e32 v133, v135
	v_cvt_f32_i32_e32 v132, v134
	v_pk_mul_f32 v[134:135], v[54:55], v[170:171] op_sel_hi:[1,0]
	s_nop 0
	v_pk_mul_f32 v[132:133], v[134:135], v[132:133]
	s_nop 0
	v_mul_f32_e32 v134, 0xbfb8aa3b, v132
	v_mul_f32_e32 v135, 0xbfb8aa3b, v133
	v_exp_f32_e32 v134, v134
	v_exp_f32_e32 v135, v135
	v_add_f32_e32 v134, 1.0, v134
	v_add_f32_e32 v135, 1.0, v135
	v_rcp_f32_e32 v134, v134
	v_rcp_f32_e32 v135, v135
	s_nop 0
	v_pk_mul_f32 v[132:133], v[132:133], v[134:135]
	v_pk_mul_f32 v[134:135], v[50:51], v[170:171] op_sel_hi:[1,0]
	s_nop 0
	v_pk_mul_f32 v[130:131], v[134:135], v[130:131]
	s_nop 0
	v_pk_mul_f32 v[134:135], v[130:131], v[132:133]
	v_cvt_pk_bf16_f32 v132, v128, v129
	v_mov_b64_e32 v[128:129], s[24:25]
	v_cvt_pk_bf16_f32 v133, v134, v135
	v_mad_i64_i32 v[134:135], s[24:25], v166, s37, v[128:129]
	v_lshl_add_u64 v[134:135], v[134:135], 0, s[22:23]
	v_lshl_add_u64 v[134:135], v[134:135], 0, s[0:1]
	v_cvt_pk_bf16_f32 v130, v136, v137
	v_cvt_pk_bf16_f32 v131, v138, v139
	v_lshl_add_u64 v[134:135], v[134:135], 0, v[156:157]
	global_store_dwordx4 v[134:135], v[130:133], off
	s_nop 1
	v_mov_b32_e32 v130, v200
	s_waitcnt vmcnt(0)
	s_nop 0
	v_or_b32_e32 v131, 16, v166
	v_pk_mul_f32 v[132:133], v[60:61], v[130:131] op_sel_hi:[1,0]
	s_nop 0
	v_pk_mul_f32 v[124:125], v[132:133], v[124:125]
	s_nop 0
	v_mul_f32_e32 v132, 0xbfb8aa3b, v124
	v_mul_f32_e32 v133, 0xbfb8aa3b, v125
	v_exp_f32_e32 v132, v132
	v_exp_f32_e32 v133, v133
	v_add_f32_e32 v132, 1.0, v132
	v_add_f32_e32 v133, 1.0, v133
	v_rcp_f32_e32 v132, v132
	v_rcp_f32_e32 v133, v133
	s_nop 0
	v_pk_mul_f32 v[124:125], v[124:125], v[132:133]
	v_pk_mul_f32 v[132:133], v[56:57], v[130:131] op_sel_hi:[1,0]
	s_nop 0
	v_pk_mul_f32 v[120:121], v[132:133], v[120:121]
	s_nop 0
	v_pk_mul_f32 v[120:121], v[120:121], v[124:125]
	v_cvt_f32_i32_e32 v125, v127
	v_cvt_f32_i32_e32 v124, v126
	v_pk_mul_f32 v[126:127], v[62:63], v[130:131] op_sel_hi:[1,0]
	s_nop 0
	v_pk_mul_f32 v[124:125], v[126:127], v[124:125]
	s_nop 0
	v_mul_f32_e32 v126, 0xbfb8aa3b, v124
	v_mul_f32_e32 v127, 0xbfb8aa3b, v125
	v_exp_f32_e32 v126, v126
	v_exp_f32_e32 v127, v127
	v_add_f32_e32 v126, 1.0, v126
	v_add_f32_e32 v127, 1.0, v127
	v_rcp_f32_e32 v126, v126
	v_rcp_f32_e32 v127, v127
	s_nop 0
	v_pk_mul_f32 v[124:125], v[124:125], v[126:127]
	v_pk_mul_f32 v[126:127], v[58:59], v[130:131] op_sel_hi:[1,0]
	s_nop 0
	v_pk_mul_f32 v[122:123], v[126:127], v[122:123]
	s_nop 0
	v_pk_mul_f32 v[122:123], v[122:123], v[124:125]
	v_pk_mul_f32 v[124:125], v[52:53], v[130:131] op_sel_hi:[1,0]
	s_nop 0
	v_pk_mul_f32 v[116:117], v[124:125], v[116:117]
	s_nop 0
	v_mul_f32_e32 v124, 0xbfb8aa3b, v116
	v_mul_f32_e32 v125, 0xbfb8aa3b, v117
	v_exp_f32_e32 v124, v124
	v_exp_f32_e32 v125, v125
	v_add_f32_e32 v124, 1.0, v124
	v_add_f32_e32 v125, 1.0, v125
	v_rcp_f32_e32 v124, v124
	v_rcp_f32_e32 v125, v125
	s_nop 0
	v_pk_mul_f32 v[116:117], v[116:117], v[124:125]
	v_pk_mul_f32 v[124:125], v[48:49], v[130:131] op_sel_hi:[1,0]
	s_nop 0
	v_pk_mul_f32 v[112:113], v[124:125], v[112:113]
	s_nop 0
	v_pk_mul_f32 v[116:117], v[112:113], v[116:117]
	v_cvt_f32_i32_e32 v113, v119
	v_cvt_f32_i32_e32 v112, v118
	v_pk_mul_f32 v[118:119], v[54:55], v[130:131] op_sel_hi:[1,0]
	s_nop 0
	v_pk_mul_f32 v[112:113], v[118:119], v[112:113]
	s_nop 0
	v_mul_f32_e32 v118, 0xbfb8aa3b, v112
	v_mul_f32_e32 v119, 0xbfb8aa3b, v113
	v_exp_f32_e32 v118, v118
	v_exp_f32_e32 v119, v119
	v_add_f32_e32 v118, 1.0, v118
	v_add_f32_e32 v119, 1.0, v119
	v_rcp_f32_e32 v118, v118
	v_rcp_f32_e32 v119, v119
	s_nop 0
	v_pk_mul_f32 v[112:113], v[112:113], v[118:119]
	v_pk_mul_f32 v[118:119], v[50:51], v[130:131] op_sel_hi:[1,0]
	s_nop 0
	v_pk_mul_f32 v[114:115], v[118:119], v[114:115]
	s_nop 0
	v_pk_mul_f32 v[118:119], v[114:115], v[112:113]
	v_cvt_pk_bf16_f32 v114, v116, v117
	v_mad_i64_i32 v[116:117], s[24:25], v131, s37, v[128:129]
	v_lshl_add_u64 v[116:117], v[116:117], 0, s[22:23]
	v_lshl_add_u64 v[116:117], v[116:117], 0, s[0:1]
	v_cvt_pk_bf16_f32 v112, v120, v121
	v_cvt_pk_bf16_f32 v113, v122, v123
	v_cvt_pk_bf16_f32 v115, v118, v119
	v_lshl_add_u64 v[116:117], v[116:117], 0, v[156:157]
	global_store_dwordx4 v[116:117], v[112:115], off
	s_nop 1
	v_mov_b32_e32 v112, v201
	s_waitcnt vmcnt(0)
	s_nop 0
	v_or_b32_e32 v113, 32, v166
	v_pk_mul_f32 v[114:115], v[60:61], v[112:113] op_sel_hi:[1,0]
	s_nop 0
	v_pk_mul_f32 v[108:109], v[114:115], v[108:109]
	s_nop 0
	v_mul_f32_e32 v114, 0xbfb8aa3b, v108
	v_mul_f32_e32 v115, 0xbfb8aa3b, v109
	v_exp_f32_e32 v114, v114
	v_exp_f32_e32 v115, v115
	v_add_f32_e32 v114, 1.0, v114
	v_add_f32_e32 v115, 1.0, v115
	v_rcp_f32_e32 v114, v114
	v_rcp_f32_e32 v115, v115
	s_nop 0
	v_pk_mul_f32 v[108:109], v[108:109], v[114:115]
	v_pk_mul_f32 v[114:115], v[56:57], v[112:113] op_sel_hi:[1,0]
	s_nop 0
	v_pk_mul_f32 v[104:105], v[114:115], v[104:105]
	s_nop 0
	v_pk_mul_f32 v[104:105], v[104:105], v[108:109]
	v_cvt_f32_i32_e32 v109, v111
	v_cvt_f32_i32_e32 v108, v110
	v_pk_mul_f32 v[110:111], v[62:63], v[112:113] op_sel_hi:[1,0]
	s_nop 0
	v_pk_mul_f32 v[108:109], v[110:111], v[108:109]
	s_nop 0
	v_mul_f32_e32 v110, 0xbfb8aa3b, v108
	v_mul_f32_e32 v111, 0xbfb8aa3b, v109
	v_exp_f32_e32 v110, v110
	v_exp_f32_e32 v111, v111
	v_add_f32_e32 v110, 1.0, v110
	v_add_f32_e32 v111, 1.0, v111
	v_rcp_f32_e32 v110, v110
	v_rcp_f32_e32 v111, v111
	s_nop 0
	v_pk_mul_f32 v[108:109], v[108:109], v[110:111]
	v_pk_mul_f32 v[110:111], v[58:59], v[112:113] op_sel_hi:[1,0]
	s_nop 0
	v_pk_mul_f32 v[106:107], v[110:111], v[106:107]
	s_nop 0
	v_pk_mul_f32 v[106:107], v[106:107], v[108:109]
	v_pk_mul_f32 v[108:109], v[52:53], v[112:113] op_sel_hi:[1,0]
	s_nop 0
	v_pk_mul_f32 v[100:101], v[108:109], v[100:101]
	s_nop 0
	v_mul_f32_e32 v108, 0xbfb8aa3b, v100
	v_mul_f32_e32 v109, 0xbfb8aa3b, v101
	v_exp_f32_e32 v108, v108
	v_exp_f32_e32 v109, v109
	v_add_f32_e32 v108, 1.0, v108
	v_add_f32_e32 v109, 1.0, v109
	v_rcp_f32_e32 v108, v108
	v_rcp_f32_e32 v109, v109
	s_nop 0
	v_pk_mul_f32 v[100:101], v[100:101], v[108:109]
	v_pk_mul_f32 v[108:109], v[48:49], v[112:113] op_sel_hi:[1,0]
	s_nop 0
	v_pk_mul_f32 v[96:97], v[108:109], v[96:97]
	s_nop 0
	v_pk_mul_f32 v[100:101], v[96:97], v[100:101]
	v_cvt_f32_i32_e32 v97, v103
	v_cvt_f32_i32_e32 v96, v102
	v_pk_mul_f32 v[102:103], v[54:55], v[112:113] op_sel_hi:[1,0]
	s_nop 0
	v_pk_mul_f32 v[96:97], v[102:103], v[96:97]
	s_nop 0
	v_mul_f32_e32 v102, 0xbfb8aa3b, v96
	v_mul_f32_e32 v103, 0xbfb8aa3b, v97
	v_exp_f32_e32 v102, v102
	v_exp_f32_e32 v103, v103
	v_add_f32_e32 v102, 1.0, v102
	v_add_f32_e32 v103, 1.0, v103
	v_rcp_f32_e32 v102, v102
	v_rcp_f32_e32 v103, v103
	s_nop 0
	v_pk_mul_f32 v[96:97], v[96:97], v[102:103]
	v_pk_mul_f32 v[102:103], v[50:51], v[112:113] op_sel_hi:[1,0]
	s_nop 0
	v_pk_mul_f32 v[98:99], v[102:103], v[98:99]
	s_nop 0
	v_pk_mul_f32 v[102:103], v[98:99], v[96:97]
	v_cvt_pk_bf16_f32 v98, v100, v101
	v_mad_i64_i32 v[100:101], s[24:25], v113, s37, v[128:129]
	v_lshl_add_u64 v[100:101], v[100:101], 0, s[22:23]
	v_lshl_add_u64 v[100:101], v[100:101], 0, s[0:1]
	v_cvt_pk_bf16_f32 v96, v104, v105
	v_cvt_pk_bf16_f32 v97, v106, v107
	v_cvt_pk_bf16_f32 v99, v102, v103
	v_lshl_add_u64 v[100:101], v[100:101], 0, v[156:157]
	global_store_dwordx4 v[100:101], v[96:99], off
	s_nop 1
	v_mov_b32_e32 v96, v202
	s_waitcnt vmcnt(0)
	s_nop 0
	v_or_b32_e32 v97, 48, v166
	v_pk_mul_f32 v[98:99], v[60:61], v[96:97] op_sel_hi:[1,0]
	s_nop 0
	v_pk_mul_f32 v[92:93], v[98:99], v[92:93]
	s_nop 0
	v_mul_f32_e32 v98, 0xbfb8aa3b, v92
	v_mul_f32_e32 v99, 0xbfb8aa3b, v93
	v_exp_f32_e32 v98, v98
	v_exp_f32_e32 v99, v99
	v_add_f32_e32 v98, 1.0, v98
	v_add_f32_e32 v99, 1.0, v99
	v_rcp_f32_e32 v98, v98
	v_rcp_f32_e32 v99, v99
	s_nop 0
	v_pk_mul_f32 v[92:93], v[92:93], v[98:99]
	v_pk_mul_f32 v[98:99], v[56:57], v[96:97] op_sel_hi:[1,0]
	s_nop 0
	v_pk_mul_f32 v[88:89], v[98:99], v[88:89]
	s_nop 0
	v_pk_mul_f32 v[88:89], v[88:89], v[92:93]
	v_cvt_f32_i32_e32 v93, v95
	v_cvt_f32_i32_e32 v92, v94
	v_pk_mul_f32 v[94:95], v[62:63], v[96:97] op_sel_hi:[1,0]
	s_nop 0
	v_pk_mul_f32 v[92:93], v[94:95], v[92:93]
	s_nop 0
	v_mul_f32_e32 v94, 0xbfb8aa3b, v92
	v_mul_f32_e32 v95, 0xbfb8aa3b, v93
	v_exp_f32_e32 v94, v94
	v_exp_f32_e32 v95, v95
	v_add_f32_e32 v94, 1.0, v94
	v_add_f32_e32 v95, 1.0, v95
	v_rcp_f32_e32 v94, v94
	v_rcp_f32_e32 v95, v95
	s_nop 0
	v_pk_mul_f32 v[92:93], v[92:93], v[94:95]
	v_pk_mul_f32 v[94:95], v[58:59], v[96:97] op_sel_hi:[1,0]
	s_nop 0
	v_pk_mul_f32 v[90:91], v[94:95], v[90:91]
	s_nop 0
	v_pk_mul_f32 v[90:91], v[90:91], v[92:93]
	v_pk_mul_f32 v[92:93], v[52:53], v[96:97] op_sel_hi:[1,0]
	s_nop 0
	v_pk_mul_f32 v[84:85], v[92:93], v[84:85]
	s_nop 0
	v_mul_f32_e32 v92, 0xbfb8aa3b, v84
	v_mul_f32_e32 v93, 0xbfb8aa3b, v85
	v_exp_f32_e32 v92, v92
	v_exp_f32_e32 v93, v93
	v_add_f32_e32 v92, 1.0, v92
	v_add_f32_e32 v93, 1.0, v93
	v_rcp_f32_e32 v92, v92
	v_rcp_f32_e32 v93, v93
	s_nop 0
	v_pk_mul_f32 v[84:85], v[84:85], v[92:93]
	v_pk_mul_f32 v[92:93], v[48:49], v[96:97] op_sel_hi:[1,0]
	s_nop 0
	v_pk_mul_f32 v[80:81], v[92:93], v[80:81]
	s_nop 0
	v_pk_mul_f32 v[84:85], v[80:81], v[84:85]
	v_cvt_f32_i32_e32 v81, v87
	v_cvt_f32_i32_e32 v80, v86
	v_pk_mul_f32 v[86:87], v[54:55], v[96:97] op_sel_hi:[1,0]
	s_nop 0
	v_pk_mul_f32 v[80:81], v[86:87], v[80:81]
	s_nop 0
	v_mul_f32_e32 v86, 0xbfb8aa3b, v80
	v_mul_f32_e32 v87, 0xbfb8aa3b, v81
	v_exp_f32_e32 v86, v86
	v_exp_f32_e32 v87, v87
	v_add_f32_e32 v86, 1.0, v86
	v_add_f32_e32 v87, 1.0, v87
	v_rcp_f32_e32 v86, v86
	v_rcp_f32_e32 v87, v87
	s_nop 0
	v_pk_mul_f32 v[80:81], v[80:81], v[86:87]
	v_pk_mul_f32 v[86:87], v[50:51], v[96:97] op_sel_hi:[1,0]
	s_nop 0
	v_pk_mul_f32 v[82:83], v[86:87], v[82:83]
	s_nop 0
	v_pk_mul_f32 v[86:87], v[82:83], v[80:81]
	v_cvt_pk_bf16_f32 v82, v84, v85
	v_mad_i64_i32 v[84:85], s[24:25], v97, s37, v[128:129]
	v_lshl_add_u64 v[84:85], v[84:85], 0, s[22:23]
	v_lshl_add_u64 v[84:85], v[84:85], 0, s[0:1]
	v_cvt_pk_bf16_f32 v80, v88, v89
	v_cvt_pk_bf16_f32 v81, v90, v91
	v_cvt_pk_bf16_f32 v83, v86, v87
	v_lshl_add_u64 v[84:85], v[84:85], 0, v[156:157]
	global_store_dwordx4 v[84:85], v[80:83], off
	s_nop 1
	v_mov_b32_e32 v80, v203
	s_waitcnt vmcnt(0)
	s_nop 0
	v_add_u32_e32 v81, 0x80, v166
	v_pk_mul_f32 v[82:83], v[60:61], v[80:81] op_sel_hi:[1,0]
	s_nop 0
	v_pk_mul_f32 v[76:77], v[82:83], v[76:77]
	s_nop 0
	v_mul_f32_e32 v82, 0xbfb8aa3b, v76
	v_mul_f32_e32 v83, 0xbfb8aa3b, v77
	v_exp_f32_e32 v82, v82
	v_exp_f32_e32 v83, v83
	v_add_f32_e32 v82, 1.0, v82
	v_add_f32_e32 v83, 1.0, v83
	v_rcp_f32_e32 v82, v82
	v_rcp_f32_e32 v83, v83
	s_nop 0
	v_pk_mul_f32 v[76:77], v[76:77], v[82:83]
	v_pk_mul_f32 v[82:83], v[56:57], v[80:81] op_sel_hi:[1,0]
	s_nop 0
	v_pk_mul_f32 v[72:73], v[82:83], v[72:73]
	s_nop 0
	v_pk_mul_f32 v[72:73], v[72:73], v[76:77]
	v_cvt_f32_i32_e32 v77, v79
	v_cvt_f32_i32_e32 v76, v78
	v_pk_mul_f32 v[78:79], v[62:63], v[80:81] op_sel_hi:[1,0]
	s_nop 0
	v_pk_mul_f32 v[76:77], v[78:79], v[76:77]
	s_nop 0
	v_mul_f32_e32 v78, 0xbfb8aa3b, v76
	v_mul_f32_e32 v79, 0xbfb8aa3b, v77
	v_exp_f32_e32 v78, v78
	v_exp_f32_e32 v79, v79
	v_add_f32_e32 v78, 1.0, v78
	v_add_f32_e32 v79, 1.0, v79
	v_rcp_f32_e32 v78, v78
	v_rcp_f32_e32 v79, v79
	s_nop 0
	v_pk_mul_f32 v[76:77], v[76:77], v[78:79]
	v_pk_mul_f32 v[78:79], v[58:59], v[80:81] op_sel_hi:[1,0]
	s_nop 0
	v_pk_mul_f32 v[74:75], v[78:79], v[74:75]
	s_nop 0
	v_pk_mul_f32 v[74:75], v[74:75], v[76:77]
	v_pk_mul_f32 v[76:77], v[52:53], v[80:81] op_sel_hi:[1,0]
	s_nop 0
	v_pk_mul_f32 v[68:69], v[76:77], v[68:69]
	s_nop 0
	v_mul_f32_e32 v76, 0xbfb8aa3b, v68
	v_mul_f32_e32 v77, 0xbfb8aa3b, v69
	v_exp_f32_e32 v76, v76
	v_exp_f32_e32 v77, v77
	v_add_f32_e32 v76, 1.0, v76
	v_add_f32_e32 v77, 1.0, v77
	v_rcp_f32_e32 v76, v76
	v_rcp_f32_e32 v77, v77
	s_nop 0
	v_pk_mul_f32 v[68:69], v[68:69], v[76:77]
	v_pk_mul_f32 v[76:77], v[48:49], v[80:81] op_sel_hi:[1,0]
	s_nop 0
	v_pk_mul_f32 v[64:65], v[76:77], v[64:65]
	s_nop 0
	v_pk_mul_f32 v[68:69], v[64:65], v[68:69]
	v_cvt_f32_i32_e32 v65, v71
	v_cvt_f32_i32_e32 v64, v70
	v_pk_mul_f32 v[70:71], v[54:55], v[80:81] op_sel_hi:[1,0]
	s_nop 0
	v_pk_mul_f32 v[64:65], v[70:71], v[64:65]
	s_nop 0
	v_mul_f32_e32 v70, 0xbfb8aa3b, v64
	v_mul_f32_e32 v71, 0xbfb8aa3b, v65
	v_exp_f32_e32 v70, v70
	v_exp_f32_e32 v71, v71
	v_add_f32_e32 v70, 1.0, v70
	v_add_f32_e32 v71, 1.0, v71
	v_rcp_f32_e32 v70, v70
	v_rcp_f32_e32 v71, v71
	s_nop 0
	v_pk_mul_f32 v[64:65], v[64:65], v[70:71]
	v_pk_mul_f32 v[70:71], v[50:51], v[80:81] op_sel_hi:[1,0]
	s_nop 0
	v_pk_mul_f32 v[66:67], v[70:71], v[66:67]
	s_nop 0
	v_pk_mul_f32 v[70:71], v[66:67], v[64:65]
	v_cvt_pk_bf16_f32 v66, v68, v69
	v_mad_i64_i32 v[68:69], s[24:25], v81, s37, v[128:129]
	v_lshl_add_u64 v[68:69], v[68:69], 0, s[22:23]
	v_lshl_add_u64 v[68:69], v[68:69], 0, s[0:1]
	v_cvt_pk_bf16_f32 v64, v72, v73
	v_cvt_pk_bf16_f32 v65, v74, v75
	v_cvt_pk_bf16_f32 v67, v70, v71
	v_lshl_add_u64 v[68:69], v[68:69], 0, v[156:157]
	global_store_dwordx4 v[68:69], v[64:67], off
	s_nop 1
	v_mov_b32_e32 v64, v204
	s_waitcnt vmcnt(0)
	s_nop 0
	v_add_u32_e32 v65, 0x90, v166
	v_pk_mul_f32 v[66:67], v[60:61], v[64:65] op_sel_hi:[1,0]
	s_nop 0
	v_pk_mul_f32 v[44:45], v[66:67], v[44:45]
	s_nop 0
	v_mul_f32_e32 v66, 0xbfb8aa3b, v44
	v_mul_f32_e32 v67, 0xbfb8aa3b, v45
	v_exp_f32_e32 v66, v66
	v_exp_f32_e32 v67, v67
	v_add_f32_e32 v66, 1.0, v66
	v_add_f32_e32 v67, 1.0, v67
	v_rcp_f32_e32 v66, v66
	v_rcp_f32_e32 v67, v67
	s_nop 0
	v_pk_mul_f32 v[44:45], v[44:45], v[66:67]
	v_pk_mul_f32 v[66:67], v[56:57], v[64:65] op_sel_hi:[1,0]
	s_nop 0
	v_pk_mul_f32 v[40:41], v[66:67], v[40:41]
	s_nop 0
	v_pk_mul_f32 v[40:41], v[40:41], v[44:45]
	v_cvt_f32_i32_e32 v45, v47
	v_cvt_f32_i32_e32 v44, v46
	v_pk_mul_f32 v[46:47], v[62:63], v[64:65] op_sel_hi:[1,0]
	s_nop 0
	v_pk_mul_f32 v[44:45], v[46:47], v[44:45]
	s_nop 0
	v_mul_f32_e32 v46, 0xbfb8aa3b, v44
	v_mul_f32_e32 v47, 0xbfb8aa3b, v45
	v_exp_f32_e32 v46, v46
	v_exp_f32_e32 v47, v47
	v_add_f32_e32 v46, 1.0, v46
	v_add_f32_e32 v47, 1.0, v47
	v_rcp_f32_e32 v46, v46
	v_rcp_f32_e32 v47, v47
	s_nop 0
	v_pk_mul_f32 v[44:45], v[44:45], v[46:47]
	v_pk_mul_f32 v[46:47], v[58:59], v[64:65] op_sel_hi:[1,0]
	s_nop 0
	v_pk_mul_f32 v[42:43], v[46:47], v[42:43]
	s_nop 0
	v_pk_mul_f32 v[42:43], v[42:43], v[44:45]
	v_pk_mul_f32 v[44:45], v[52:53], v[64:65] op_sel_hi:[1,0]
	s_nop 0
	v_pk_mul_f32 v[36:37], v[44:45], v[36:37]
	s_nop 0
	v_mul_f32_e32 v44, 0xbfb8aa3b, v36
	v_mul_f32_e32 v45, 0xbfb8aa3b, v37
	v_exp_f32_e32 v44, v44
	v_exp_f32_e32 v45, v45
	v_add_f32_e32 v44, 1.0, v44
	v_add_f32_e32 v45, 1.0, v45
	v_rcp_f32_e32 v44, v44
	v_rcp_f32_e32 v45, v45
	s_nop 0
	v_pk_mul_f32 v[36:37], v[36:37], v[44:45]
	v_pk_mul_f32 v[44:45], v[48:49], v[64:65] op_sel_hi:[1,0]
	s_nop 0
	v_pk_mul_f32 v[32:33], v[44:45], v[32:33]
	s_nop 0
	v_pk_mul_f32 v[36:37], v[32:33], v[36:37]
	v_cvt_f32_i32_e32 v33, v39
	v_cvt_f32_i32_e32 v32, v38
	v_pk_mul_f32 v[38:39], v[54:55], v[64:65] op_sel_hi:[1,0]
	s_nop 0
	v_pk_mul_f32 v[32:33], v[38:39], v[32:33]
	s_nop 0
	v_mul_f32_e32 v38, 0xbfb8aa3b, v32
	v_mul_f32_e32 v39, 0xbfb8aa3b, v33
	v_exp_f32_e32 v38, v38
	v_exp_f32_e32 v39, v39
	v_add_f32_e32 v38, 1.0, v38
	v_add_f32_e32 v39, 1.0, v39
	v_rcp_f32_e32 v38, v38
	v_rcp_f32_e32 v39, v39
	s_nop 0
	v_pk_mul_f32 v[32:33], v[32:33], v[38:39]
	v_pk_mul_f32 v[38:39], v[50:51], v[64:65] op_sel_hi:[1,0]
	s_nop 0
	v_pk_mul_f32 v[34:35], v[38:39], v[34:35]
	s_nop 0
	v_pk_mul_f32 v[38:39], v[34:35], v[32:33]
	v_cvt_pk_bf16_f32 v34, v36, v37
	v_mad_i64_i32 v[36:37], s[24:25], v65, s37, v[128:129]
	v_lshl_add_u64 v[36:37], v[36:37], 0, s[22:23]
	v_lshl_add_u64 v[36:37], v[36:37], 0, s[0:1]
	v_cvt_pk_bf16_f32 v32, v40, v41
	v_cvt_pk_bf16_f32 v33, v42, v43
	v_cvt_pk_bf16_f32 v35, v38, v39
	v_lshl_add_u64 v[36:37], v[36:37], 0, v[156:157]
	global_store_dwordx4 v[36:37], v[32:35], off
	s_nop 1
	v_mov_b32_e32 v32, v205
	s_waitcnt vmcnt(0)
	s_nop 0
	v_add_u32_e32 v33, 0xa0, v166
	v_pk_mul_f32 v[34:35], v[60:61], v[32:33] op_sel_hi:[1,0]
	s_nop 0
	v_pk_mul_f32 v[28:29], v[34:35], v[28:29]
	s_nop 0
	v_mul_f32_e32 v34, 0xbfb8aa3b, v28
	v_mul_f32_e32 v35, 0xbfb8aa3b, v29
	v_exp_f32_e32 v34, v34
	v_exp_f32_e32 v35, v35
	v_add_f32_e32 v34, 1.0, v34
	v_add_f32_e32 v35, 1.0, v35
	v_rcp_f32_e32 v34, v34
	v_rcp_f32_e32 v35, v35
	s_nop 0
	v_pk_mul_f32 v[28:29], v[28:29], v[34:35]
	v_pk_mul_f32 v[34:35], v[56:57], v[32:33] op_sel_hi:[1,0]
	s_nop 0
	v_pk_mul_f32 v[24:25], v[34:35], v[24:25]
	s_nop 0
	v_pk_mul_f32 v[24:25], v[24:25], v[28:29]
	v_cvt_f32_i32_e32 v29, v31
	v_cvt_f32_i32_e32 v28, v30
	v_pk_mul_f32 v[30:31], v[62:63], v[32:33] op_sel_hi:[1,0]
	s_nop 0
	v_pk_mul_f32 v[28:29], v[30:31], v[28:29]
	s_nop 0
	v_mul_f32_e32 v30, 0xbfb8aa3b, v28
	v_mul_f32_e32 v31, 0xbfb8aa3b, v29
	v_exp_f32_e32 v30, v30
	v_exp_f32_e32 v31, v31
	v_add_f32_e32 v30, 1.0, v30
	v_add_f32_e32 v31, 1.0, v31
	v_rcp_f32_e32 v30, v30
	v_rcp_f32_e32 v31, v31
	s_nop 0
	v_pk_mul_f32 v[28:29], v[28:29], v[30:31]
	v_pk_mul_f32 v[30:31], v[58:59], v[32:33] op_sel_hi:[1,0]
	s_nop 0
	v_pk_mul_f32 v[26:27], v[30:31], v[26:27]
	s_nop 0
	v_pk_mul_f32 v[26:27], v[26:27], v[28:29]
	v_pk_mul_f32 v[28:29], v[52:53], v[32:33] op_sel_hi:[1,0]
	s_nop 0
	v_pk_mul_f32 v[20:21], v[28:29], v[20:21]
	s_nop 0
	v_mul_f32_e32 v28, 0xbfb8aa3b, v20
	v_mul_f32_e32 v29, 0xbfb8aa3b, v21
	v_exp_f32_e32 v28, v28
	v_exp_f32_e32 v29, v29
	v_add_f32_e32 v28, 1.0, v28
	v_add_f32_e32 v29, 1.0, v29
	v_rcp_f32_e32 v28, v28
	v_rcp_f32_e32 v29, v29
	s_nop 0
	v_pk_mul_f32 v[20:21], v[20:21], v[28:29]
	v_pk_mul_f32 v[28:29], v[48:49], v[32:33] op_sel_hi:[1,0]
	s_nop 0
	v_pk_mul_f32 v[16:17], v[28:29], v[16:17]
	s_nop 0
	v_pk_mul_f32 v[20:21], v[16:17], v[20:21]
	v_cvt_f32_i32_e32 v17, v23
	v_cvt_f32_i32_e32 v16, v22
	v_pk_mul_f32 v[22:23], v[54:55], v[32:33] op_sel_hi:[1,0]
	s_nop 0
	v_pk_mul_f32 v[16:17], v[22:23], v[16:17]
	s_nop 0
	v_mul_f32_e32 v22, 0xbfb8aa3b, v16
	v_mul_f32_e32 v23, 0xbfb8aa3b, v17
	v_exp_f32_e32 v22, v22
	v_exp_f32_e32 v23, v23
	v_add_f32_e32 v22, 1.0, v22
	v_add_f32_e32 v23, 1.0, v23
	v_rcp_f32_e32 v22, v22
	v_rcp_f32_e32 v23, v23
	s_nop 0
	v_pk_mul_f32 v[16:17], v[16:17], v[22:23]
	v_pk_mul_f32 v[22:23], v[50:51], v[32:33] op_sel_hi:[1,0]
	s_nop 0
	v_pk_mul_f32 v[18:19], v[22:23], v[18:19]
	s_nop 0
	v_pk_mul_f32 v[22:23], v[18:19], v[16:17]
	v_cvt_pk_bf16_f32 v18, v20, v21
	v_mad_i64_i32 v[20:21], s[24:25], v33, s37, v[128:129]
	v_lshl_add_u64 v[20:21], v[20:21], 0, s[22:23]
	v_lshl_add_u64 v[20:21], v[20:21], 0, s[0:1]
	v_cvt_pk_bf16_f32 v16, v24, v25
	v_cvt_pk_bf16_f32 v17, v26, v27
	v_cvt_pk_bf16_f32 v19, v22, v23
	v_lshl_add_u64 v[20:21], v[20:21], 0, v[156:157]
	global_store_dwordx4 v[20:21], v[16:19], off
	s_nop 1
	v_mov_b32_e32 v16, v206
	s_waitcnt vmcnt(0)
	s_nop 0
	v_add_u32_e32 v17, 0xb0, v166
	v_pk_mul_f32 v[18:19], v[60:61], v[16:17] op_sel_hi:[1,0]
	s_nop 0
	v_pk_mul_f32 v[12:13], v[18:19], v[12:13]
	s_nop 0
	v_mul_f32_e32 v18, 0xbfb8aa3b, v12
	v_mul_f32_e32 v19, 0xbfb8aa3b, v13
	v_exp_f32_e32 v18, v18
	v_exp_f32_e32 v19, v19
	v_add_f32_e32 v18, 1.0, v18
	v_add_f32_e32 v19, 1.0, v19
	v_rcp_f32_e32 v18, v18
	v_rcp_f32_e32 v19, v19
	s_nop 0
	v_pk_mul_f32 v[12:13], v[12:13], v[18:19]
	v_pk_mul_f32 v[18:19], v[56:57], v[16:17] op_sel_hi:[1,0]
	s_nop 0
	v_pk_mul_f32 v[8:9], v[18:19], v[8:9]
	s_nop 0
	v_pk_mul_f32 v[8:9], v[8:9], v[12:13]
	v_cvt_f32_i32_e32 v13, v15
	v_cvt_f32_i32_e32 v12, v14
	v_pk_mul_f32 v[14:15], v[62:63], v[16:17] op_sel_hi:[1,0]
	s_nop 0
	v_pk_mul_f32 v[12:13], v[14:15], v[12:13]
	s_nop 0
	v_mul_f32_e32 v14, 0xbfb8aa3b, v12
	v_mul_f32_e32 v15, 0xbfb8aa3b, v13
	v_exp_f32_e32 v14, v14
	v_exp_f32_e32 v15, v15
	v_add_f32_e32 v14, 1.0, v14
	v_add_f32_e32 v15, 1.0, v15
	v_rcp_f32_e32 v14, v14
	v_rcp_f32_e32 v15, v15
	s_nop 0
	v_pk_mul_f32 v[12:13], v[12:13], v[14:15]
	v_pk_mul_f32 v[14:15], v[58:59], v[16:17] op_sel_hi:[1,0]
	s_nop 0
	v_pk_mul_f32 v[10:11], v[14:15], v[10:11]
	s_nop 0
	v_pk_mul_f32 v[10:11], v[10:11], v[12:13]
	v_pk_mul_f32 v[12:13], v[52:53], v[16:17] op_sel_hi:[1,0]
	s_nop 0
	v_pk_mul_f32 v[4:5], v[12:13], v[4:5]
	s_nop 0
	v_mul_f32_e32 v12, 0xbfb8aa3b, v4
	v_mul_f32_e32 v13, 0xbfb8aa3b, v5
	v_exp_f32_e32 v12, v12
	v_exp_f32_e32 v13, v13
	v_add_f32_e32 v12, 1.0, v12
	v_add_f32_e32 v13, 1.0, v13
	v_rcp_f32_e32 v12, v12
	v_rcp_f32_e32 v13, v13
	s_nop 0
	v_pk_mul_f32 v[4:5], v[4:5], v[12:13]
	v_pk_mul_f32 v[12:13], v[48:49], v[16:17] op_sel_hi:[1,0]
	s_nop 0
	v_pk_mul_f32 v[0:1], v[12:13], v[0:1]
	s_nop 0
	v_pk_mul_f32 v[4:5], v[0:1], v[4:5]
	v_cvt_f32_i32_e32 v1, v7
	v_cvt_f32_i32_e32 v0, v6
	v_pk_mul_f32 v[6:7], v[54:55], v[16:17] op_sel_hi:[1,0]
	s_nop 0
	v_pk_mul_f32 v[0:1], v[6:7], v[0:1]
	s_nop 0
	v_mul_f32_e32 v6, 0xbfb8aa3b, v0
	v_mul_f32_e32 v7, 0xbfb8aa3b, v1
	v_exp_f32_e32 v6, v6
	v_exp_f32_e32 v7, v7
	v_add_f32_e32 v6, 1.0, v6
	v_add_f32_e32 v7, 1.0, v7
	v_rcp_f32_e32 v6, v6
	v_rcp_f32_e32 v7, v7
	s_nop 0
	v_pk_mul_f32 v[0:1], v[0:1], v[6:7]
	v_pk_mul_f32 v[6:7], v[50:51], v[16:17] op_sel_hi:[1,0]
	s_nop 0
	v_pk_mul_f32 v[2:3], v[6:7], v[2:3]
	s_nop 0
	v_pk_mul_f32 v[6:7], v[2:3], v[0:1]
	v_cvt_pk_bf16_f32 v2, v4, v5
	v_mad_i64_i32 v[4:5], s[24:25], v17, s37, v[128:129]
	v_lshl_add_u64 v[4:5], v[4:5], 0, s[22:23]
	v_lshl_add_u64 v[4:5], v[4:5], 0, s[0:1]
	v_cvt_pk_bf16_f32 v0, v8, v9
	v_cvt_pk_bf16_f32 v1, v10, v11
	v_cvt_pk_bf16_f32 v3, v6, v7
	v_lshl_add_u64 v[4:5], v[4:5], 0, v[156:157]
	s_mov_b64 s[22:23], -1
	global_store_dwordx4 v[4:5], v[0:3], off
	s_cbranch_vccnz .LBB0_1962
	s_andn2_b64 vcc, exec, s[2:3]
	s_cbranch_vccnz .LBB0_1961
	s_barrier
	s_branch .LBB0_1961
